# hand-written norm_in row loop (gain once per wave, shift/scale once per row pair, loads one pair ahead) with non-temporal loads of the f32 input; non-temporal loads of the once-read rows in the gated-
# speedup vs baseline: 1.0762x; 1.0093x over previous
.LBB0_92:
	s_or_b64 exec, exec, s[2:3]
	s_mov_b64 s[2:3], s[0:1]
	v_mov_b32_e32 v1, v184
	v_mov_b32_e32 v0, v184
	s_barrier
	s_lshl_b32 s6, s72, 3
	s_mov_b32 s4, s6
	v_ashrrev_i32_e32 v0, 6, v0
	v_add_u32_e32 v2, s6, v0
	v_writelane_b32 v255, s4, 0
	s_mov_b32 s24, 0x8800
	s_lshl_b32 s66, s33, 3
	v_writelane_b32 v255, s5, 1
	v_cmp_gt_i32_e32 vcc, s24, v2
	v_mbcnt_lo_u32_b32 v3, -1, 0
	s_and_saveexec_b64 s[6:7], vcc
	s_cbranch_execz .LBB0_103
	s_load_dwordx2 s[4:5], s[2:3], 0x0
	s_load_dwordx2 s[14:15], s[2:3], 0x10
	s_load_dwordx2 s[12:13], s[2:3], 0x30
	s_load_dwordx2 s[8:9], s[2:3], 0xc0
	s_mov_b32 s67, 0
	v_and_b32_e32 v1, 63, v184
	v_lshlrev_b32_e32 v4, 5, v1
	v_lshlrev_b32_e32 v5, 4, v1
	v_readfirstlane_b32 s16, v2
	s_mov_b32 s17, 0
	s_nop 3
	s_waitcnt lgkmcnt(0)
	s_lshl_b64 s[18:19], s[16:17], 12
	s_add_u32 s10, s18, s14
	s_addc_u32 s11, s19, s15
	s_add_u32 s18, s18, s4
	s_addc_u32 s19, s19, s5
	s_add_u32 s26, s18, 0x800000
	s_addc_u32 s27, s19, 0
	s_add_u32 s20, s8, 0xe00000
	s_addc_u32 s21, s9, 0
	s_lshl_b64 s[22:23], s[16:17], 11
	s_add_u32 s22, s22, s8
	s_addc_u32 s23, s23, s9
	s_add_u32 s2, s22, 0x6400000
	s_addc_u32 s3, s23, 0
	s_add_u32 s22, s22, 0x2400000
	s_addc_u32 s23, s23, 0
	s_add_u32 s28, s22, 0x400000
	s_addc_u32 s29, s23, 0
	global_load_dwordx4 v[8:11], v4, s[12:13]
	global_load_dwordx4 v[12:15], v4, s[12:13] offset:16
	global_load_dwordx4 v[16:19], v4, s[12:13] offset:2048
	global_load_dwordx4 v[20:23], v4, s[12:13] offset:2064
	s_add_u32 s12, s20, 0x1000
	s_addc_u32 s13, s21, 0
	global_load_dwordx4 v[24:27], v4, s[18:19] nt
	global_load_dwordx4 v[28:31], v4, s[18:19] offset:16 nt
	global_load_dwordx4 v[32:35], v4, s[18:19] offset:2048 nt
	global_load_dwordx4 v[36:39], v4, s[18:19] offset:2064 nt
	global_load_dwordx4 v[40:43], v4, s[26:27] nt
	global_load_dwordx4 v[44:47], v4, s[26:27] offset:16 nt
	global_load_dwordx4 v[48:51], v4, s[26:27] offset:2048 nt
	global_load_dwordx4 v[52:55], v4, s[26:27] offset:2064 nt
	global_load_dwordx4 v[56:59], v4, s[20:21]
	global_load_dwordx4 v[60:63], v4, s[20:21] offset:16
	global_load_dwordx4 v[64:67], v4, s[20:21] offset:2048
	global_load_dwordx4 v[68:71], v4, s[20:21] offset:2064
	global_load_dwordx4 v[72:75], v4, s[12:13]
	global_load_dwordx4 v[76:79], v4, s[12:13] offset:16
	global_load_dwordx4 v[80:83], v4, s[12:13] offset:2048
	global_load_dwordx4 v[84:87], v4, s[12:13] offset:2064
	s_add_u32 s18, s18, 0x1000000
	s_addc_u32 s19, s19, 0
	s_add_u32 s26, s26, 0x1000000
	s_addc_u32 s27, s27, 0
	s_add_u32 s20, s20, 0x6000
	s_addc_u32 s21, s21, 0
	s_add_u32 s12, s12, 0x6000
	s_addc_u32 s13, s13, 0
	global_load_dwordx4 v[88:91], v4, s[18:19] nt
	global_load_dwordx4 v[92:95], v4, s[18:19] offset:16 nt
	global_load_dwordx4 v[96:99], v4, s[18:19] offset:2048 nt
	global_load_dwordx4 v[100:103], v4, s[18:19] offset:2064 nt
	global_load_dwordx4 v[104:107], v4, s[26:27] nt
	global_load_dwordx4 v[108:111], v4, s[26:27] offset:16 nt
	global_load_dwordx4 v[112:115], v4, s[26:27] offset:2048 nt
	global_load_dwordx4 v[116:119], v4, s[26:27] offset:2064 nt
	global_load_dwordx4 v[120:123], v4, s[20:21]
	global_load_dwordx4 v[124:127], v4, s[20:21] offset:16
	global_load_dwordx4 v[128:131], v4, s[20:21] offset:2048
	global_load_dwordx4 v[132:135], v4, s[20:21] offset:2064
	global_load_dwordx4 v[136:139], v4, s[12:13]
	global_load_dwordx4 v[140:143], v4, s[12:13] offset:16
	global_load_dwordx4 v[144:147], v4, s[12:13] offset:2048
	global_load_dwordx4 v[148:151], v4, s[12:13] offset:2064
	s_add_u32 s18, s18, 0x1000000
	s_addc_u32 s19, s19, 0
	s_add_u32 s26, s26, 0x1000000
	s_addc_u32 s27, s27, 0
	s_add_u32 s20, s20, 0x6000
	s_addc_u32 s21, s21, 0
	s_add_u32 s12, s12, 0x6000
	s_addc_u32 s13, s13, 0
	s_waitcnt vmcnt(16)
	v_mul_f32_e32 v152, v24, v24
	v_fmac_f32_e32 v152, v25, v25
	v_fmac_f32_e32 v152, v26, v26
	v_fmac_f32_e32 v152, v27, v27
	v_fmac_f32_e32 v152, v28, v28
	v_fmac_f32_e32 v152, v29, v29
	v_fmac_f32_e32 v152, v30, v30
	v_fmac_f32_e32 v152, v31, v31
	v_fmac_f32_e32 v152, v32, v32
	v_fmac_f32_e32 v152, v33, v33
	v_fmac_f32_e32 v152, v34, v34
	v_fmac_f32_e32 v152, v35, v35
	v_fmac_f32_e32 v152, v36, v36
	v_fmac_f32_e32 v152, v37, v37
	v_fmac_f32_e32 v152, v38, v38
	v_fmac_f32_e32 v152, v39, v39
	v_mov_b32_e32 v153, v152
	s_nop 1
	v_permlane32_swap_b32_e32 v152, v153
	v_add_f32_e32 v152, v152, v153
	v_mov_b32_e32 v153, v152
	s_nop 1
	v_permlane16_swap_b32_e32 v152, v153
	v_add_f32_e32 v152, v152, v153
	s_nop 1
	v_mov_b32_dpp v153, v152 row_ror:8 row_mask:0xf bank_mask:0xf
	v_add_f32_e32 v152, v152, v153
	s_nop 1
	v_mov_b32_dpp v153, v152 row_ror:4 row_mask:0xf bank_mask:0xf
	v_add_f32_e32 v152, v152, v153
	s_nop 1
	v_mov_b32_dpp v153, v152 row_ror:2 row_mask:0xf bank_mask:0xf
	v_add_f32_e32 v152, v152, v153
	s_nop 1
	v_mov_b32_dpp v153, v152 row_ror:1 row_mask:0xf bank_mask:0xf
	v_add_f32_e32 v152, v152, v153
	v_mov_b32_e32 v153, 0x358637bd
	v_fmac_f32_e32 v153, 0x3a800000, v152
	v_rsq_f32_e32 v153, v153
	s_nop 0
	v_mul_f32_e32 v156, v24, v153
	v_mul_f32_e32 v157, v25, v153
	v_mul_f32_e32 v158, v26, v153
	v_mul_f32_e32 v159, v27, v153
	v_mul_f32_e32 v160, v28, v153
	v_mul_f32_e32 v161, v29, v153
	v_mul_f32_e32 v162, v30, v153
	v_mul_f32_e32 v163, v31, v153
	v_mul_f32_e32 v164, v32, v153
	v_mul_f32_e32 v165, v33, v153
	v_mul_f32_e32 v166, v34, v153
	v_mul_f32_e32 v167, v35, v153
	v_mul_f32_e32 v168, v36, v153
	v_mul_f32_e32 v169, v37, v153
	v_mul_f32_e32 v170, v38, v153
	v_mul_f32_e32 v171, v39, v153
	v_mul_f32_e32 v156, v156, v8
	v_mul_f32_e32 v157, v157, v9
	v_mul_f32_e32 v158, v158, v10
	v_mul_f32_e32 v159, v159, v11
	v_mul_f32_e32 v160, v160, v12
	v_mul_f32_e32 v161, v161, v13
	v_mul_f32_e32 v162, v162, v14
	v_mul_f32_e32 v163, v163, v15
	v_mul_f32_e32 v164, v164, v16
	v_mul_f32_e32 v165, v165, v17
	v_mul_f32_e32 v166, v166, v18
	v_mul_f32_e32 v167, v167, v19
	v_mul_f32_e32 v168, v168, v20
	v_mul_f32_e32 v169, v169, v21
	v_mul_f32_e32 v170, v170, v22
	v_mul_f32_e32 v171, v171, v23
	v_add_f32_e32 v24, 1.0, v72
	v_add_f32_e32 v25, 1.0, v73
	v_add_f32_e32 v26, 1.0, v74
	v_add_f32_e32 v27, 1.0, v75
	v_add_f32_e32 v28, 1.0, v76
	v_add_f32_e32 v29, 1.0, v77
	v_add_f32_e32 v30, 1.0, v78
	v_add_f32_e32 v31, 1.0, v79
	v_add_f32_e32 v32, 1.0, v80
	v_add_f32_e32 v33, 1.0, v81
	v_add_f32_e32 v34, 1.0, v82
	v_add_f32_e32 v35, 1.0, v83
	v_add_f32_e32 v36, 1.0, v84
	v_add_f32_e32 v37, 1.0, v85
	v_add_f32_e32 v38, 1.0, v86
	v_add_f32_e32 v39, 1.0, v87
	v_fma_f32 v156, v156, v24, v56
	v_fma_f32 v157, v157, v25, v57
	v_fma_f32 v158, v158, v26, v58
	v_fma_f32 v159, v159, v27, v59
	v_fma_f32 v160, v160, v28, v60
	v_fma_f32 v161, v161, v29, v61
	v_fma_f32 v162, v162, v30, v62
	v_fma_f32 v163, v163, v31, v63
	v_fma_f32 v164, v164, v32, v64
	v_fma_f32 v165, v165, v33, v65
	v_fma_f32 v166, v166, v34, v66
	v_fma_f32 v167, v167, v35, v67
	v_fma_f32 v168, v168, v36, v68
	v_fma_f32 v169, v169, v37, v69
	v_fma_f32 v170, v170, v38, v70
	v_fma_f32 v171, v171, v39, v71
	v_cvt_pk_bf16_f32 v156, v156, v157
	v_cvt_pk_bf16_f32 v157, v158, v159
	v_cvt_pk_bf16_f32 v158, v160, v161
	v_cvt_pk_bf16_f32 v159, v162, v163
	v_cvt_pk_bf16_f32 v160, v164, v165
	v_cvt_pk_bf16_f32 v161, v166, v167
	v_cvt_pk_bf16_f32 v162, v168, v169
	v_cvt_pk_bf16_f32 v163, v170, v171
	global_store_dwordx4 v5, v[156:159], s[22:23]
	global_store_dwordx4 v5, v[160:163], s[22:23] offset:1024
	v_mul_f32_e32 v152, v40, v40
	v_fmac_f32_e32 v152, v41, v41
	v_fmac_f32_e32 v152, v42, v42
	v_fmac_f32_e32 v152, v43, v43
	v_fmac_f32_e32 v152, v44, v44
	v_fmac_f32_e32 v152, v45, v45
	v_fmac_f32_e32 v152, v46, v46
	v_fmac_f32_e32 v152, v47, v47
	v_fmac_f32_e32 v152, v48, v48
	v_fmac_f32_e32 v152, v49, v49
	v_fmac_f32_e32 v152, v50, v50
	v_fmac_f32_e32 v152, v51, v51
	v_fmac_f32_e32 v152, v52, v52
	v_fmac_f32_e32 v152, v53, v53
	v_fmac_f32_e32 v152, v54, v54
	v_fmac_f32_e32 v152, v55, v55
	v_mov_b32_e32 v153, v152
	s_nop 1
	v_permlane32_swap_b32_e32 v152, v153
	v_add_f32_e32 v152, v152, v153
	v_mov_b32_e32 v153, v152
	s_nop 1
	v_permlane16_swap_b32_e32 v152, v153
	v_add_f32_e32 v152, v152, v153
	s_nop 1
	v_mov_b32_dpp v153, v152 row_ror:8 row_mask:0xf bank_mask:0xf
	v_add_f32_e32 v152, v152, v153
	s_nop 1
	v_mov_b32_dpp v153, v152 row_ror:4 row_mask:0xf bank_mask:0xf
	v_add_f32_e32 v152, v152, v153
	s_nop 1
	v_mov_b32_dpp v153, v152 row_ror:2 row_mask:0xf bank_mask:0xf
	v_add_f32_e32 v152, v152, v153
	s_nop 1
	v_mov_b32_dpp v153, v152 row_ror:1 row_mask:0xf bank_mask:0xf
	v_add_f32_e32 v152, v152, v153
	v_mov_b32_e32 v153, 0x358637bd
	v_fmac_f32_e32 v153, 0x3a800000, v152
	v_rsq_f32_e32 v153, v153
	s_nop 0
	v_mul_f32_e32 v156, v40, v153
	v_mul_f32_e32 v157, v41, v153
	v_mul_f32_e32 v158, v42, v153
	v_mul_f32_e32 v159, v43, v153
	v_mul_f32_e32 v160, v44, v153
	v_mul_f32_e32 v161, v45, v153
	v_mul_f32_e32 v162, v46, v153
	v_mul_f32_e32 v163, v47, v153
	v_mul_f32_e32 v164, v48, v153
	v_mul_f32_e32 v165, v49, v153
	v_mul_f32_e32 v166, v50, v153
	v_mul_f32_e32 v167, v51, v153
	v_mul_f32_e32 v168, v52, v153
	v_mul_f32_e32 v169, v53, v153
	v_mul_f32_e32 v170, v54, v153
	v_mul_f32_e32 v171, v55, v153
	v_mul_f32_e32 v156, v156, v8
	v_mul_f32_e32 v157, v157, v9
	v_mul_f32_e32 v158, v158, v10
	v_mul_f32_e32 v159, v159, v11
	v_mul_f32_e32 v160, v160, v12
	v_mul_f32_e32 v161, v161, v13
	v_mul_f32_e32 v162, v162, v14
	v_mul_f32_e32 v163, v163, v15
	v_mul_f32_e32 v164, v164, v16
	v_mul_f32_e32 v165, v165, v17
	v_mul_f32_e32 v166, v166, v18
	v_mul_f32_e32 v167, v167, v19
	v_mul_f32_e32 v168, v168, v20
	v_mul_f32_e32 v169, v169, v21
	v_mul_f32_e32 v170, v170, v22
	v_mul_f32_e32 v171, v171, v23
	v_add_f32_e32 v40, 1.0, v72
	v_add_f32_e32 v41, 1.0, v73
	v_add_f32_e32 v42, 1.0, v74
	v_add_f32_e32 v43, 1.0, v75
	v_add_f32_e32 v44, 1.0, v76
	v_add_f32_e32 v45, 1.0, v77
	v_add_f32_e32 v46, 1.0, v78
	v_add_f32_e32 v47, 1.0, v79
	v_add_f32_e32 v48, 1.0, v80
	v_add_f32_e32 v49, 1.0, v81
	v_add_f32_e32 v50, 1.0, v82
	v_add_f32_e32 v51, 1.0, v83
	v_add_f32_e32 v52, 1.0, v84
	v_add_f32_e32 v53, 1.0, v85
	v_add_f32_e32 v54, 1.0, v86
	v_add_f32_e32 v55, 1.0, v87
	v_fma_f32 v156, v156, v40, v56
	v_fma_f32 v157, v157, v41, v57
	v_fma_f32 v158, v158, v42, v58
	v_fma_f32 v159, v159, v43, v59
	v_fma_f32 v160, v160, v44, v60
	v_fma_f32 v161, v161, v45, v61
	v_fma_f32 v162, v162, v46, v62
	v_fma_f32 v163, v163, v47, v63
	v_fma_f32 v164, v164, v48, v64
	v_fma_f32 v165, v165, v49, v65
	v_fma_f32 v166, v166, v50, v66
	v_fma_f32 v167, v167, v51, v67
	v_fma_f32 v168, v168, v52, v68
	v_fma_f32 v169, v169, v53, v69
	v_fma_f32 v170, v170, v54, v70
	v_fma_f32 v171, v171, v55, v71
	v_cvt_pk_bf16_f32 v156, v156, v157
	v_cvt_pk_bf16_f32 v157, v158, v159
	v_cvt_pk_bf16_f32 v158, v160, v161
	v_cvt_pk_bf16_f32 v159, v162, v163
	v_cvt_pk_bf16_f32 v160, v164, v165
	v_cvt_pk_bf16_f32 v161, v166, v167
	v_cvt_pk_bf16_f32 v162, v168, v169
	v_cvt_pk_bf16_f32 v163, v170, v171
	global_store_dwordx4 v5, v[156:159], s[28:29]
	global_store_dwordx4 v5, v[160:163], s[28:29] offset:1024
	s_add_u32 s22, s22, 0x800000
	s_addc_u32 s23, s23, 0
	s_add_u32 s28, s28, 0x800000
	s_addc_u32 s29, s29, 0
	global_load_dwordx4 v[24:27], v4, s[18:19] nt
	global_load_dwordx4 v[28:31], v4, s[18:19] offset:16 nt
	global_load_dwordx4 v[32:35], v4, s[18:19] offset:2048 nt
	global_load_dwordx4 v[36:39], v4, s[18:19] offset:2064 nt
	global_load_dwordx4 v[40:43], v4, s[26:27] nt
	global_load_dwordx4 v[44:47], v4, s[26:27] offset:16 nt
	global_load_dwordx4 v[48:51], v4, s[26:27] offset:2048 nt
	global_load_dwordx4 v[52:55], v4, s[26:27] offset:2064 nt
	global_load_dwordx4 v[56:59], v4, s[20:21]
	global_load_dwordx4 v[60:63], v4, s[20:21] offset:16
	global_load_dwordx4 v[64:67], v4, s[20:21] offset:2048
	global_load_dwordx4 v[68:71], v4, s[20:21] offset:2064
	global_load_dwordx4 v[72:75], v4, s[12:13]
	global_load_dwordx4 v[76:79], v4, s[12:13] offset:16
	global_load_dwordx4 v[80:83], v4, s[12:13] offset:2048
	global_load_dwordx4 v[84:87], v4, s[12:13] offset:2064
	s_add_u32 s18, s18, 0x1000000
	s_addc_u32 s19, s19, 0
	s_add_u32 s26, s26, 0x1000000
	s_addc_u32 s27, s27, 0
	s_add_u32 s20, s20, 0x6000
	s_addc_u32 s21, s21, 0
	s_add_u32 s12, s12, 0x6000
	s_addc_u32 s13, s13, 0
	s_waitcnt vmcnt(20)
	v_mul_f32_e32 v152, v88, v88
	v_fmac_f32_e32 v152, v89, v89
	v_fmac_f32_e32 v152, v90, v90
	v_fmac_f32_e32 v152, v91, v91
	v_fmac_f32_e32 v152, v92, v92
	v_fmac_f32_e32 v152, v93, v93
	v_fmac_f32_e32 v152, v94, v94
	v_fmac_f32_e32 v152, v95, v95
	v_fmac_f32_e32 v152, v96, v96
	v_fmac_f32_e32 v152, v97, v97
	v_fmac_f32_e32 v152, v98, v98
	v_fmac_f32_e32 v152, v99, v99
	v_fmac_f32_e32 v152, v100, v100
	v_fmac_f32_e32 v152, v101, v101
	v_fmac_f32_e32 v152, v102, v102
	v_fmac_f32_e32 v152, v103, v103
	v_mov_b32_e32 v153, v152
	s_nop 1
	v_permlane32_swap_b32_e32 v152, v153
	v_add_f32_e32 v152, v152, v153
	v_mov_b32_e32 v153, v152
	s_nop 1
	v_permlane16_swap_b32_e32 v152, v153
	v_add_f32_e32 v152, v152, v153
	s_nop 1
	v_mov_b32_dpp v153, v152 row_ror:8 row_mask:0xf bank_mask:0xf
	v_add_f32_e32 v152, v152, v153
	s_nop 1
	v_mov_b32_dpp v153, v152 row_ror:4 row_mask:0xf bank_mask:0xf
	v_add_f32_e32 v152, v152, v153
	s_nop 1
	v_mov_b32_dpp v153, v152 row_ror:2 row_mask:0xf bank_mask:0xf
	v_add_f32_e32 v152, v152, v153
	s_nop 1
	v_mov_b32_dpp v153, v152 row_ror:1 row_mask:0xf bank_mask:0xf
	v_add_f32_e32 v152, v152, v153
	v_mov_b32_e32 v153, 0x358637bd
	v_fmac_f32_e32 v153, 0x3a800000, v152
	v_rsq_f32_e32 v153, v153
	s_nop 0
	v_mul_f32_e32 v156, v88, v153
	v_mul_f32_e32 v157, v89, v153
	v_mul_f32_e32 v158, v90, v153
	v_mul_f32_e32 v159, v91, v153
	v_mul_f32_e32 v160, v92, v153
	v_mul_f32_e32 v161, v93, v153
	v_mul_f32_e32 v162, v94, v153
	v_mul_f32_e32 v163, v95, v153
	v_mul_f32_e32 v164, v96, v153
	v_mul_f32_e32 v165, v97, v153
	v_mul_f32_e32 v166, v98, v153
	v_mul_f32_e32 v167, v99, v153
	v_mul_f32_e32 v168, v100, v153
	v_mul_f32_e32 v169, v101, v153
	v_mul_f32_e32 v170, v102, v153
	v_mul_f32_e32 v171, v103, v153
	v_mul_f32_e32 v156, v156, v8
	v_mul_f32_e32 v157, v157, v9
	v_mul_f32_e32 v158, v158, v10
	v_mul_f32_e32 v159, v159, v11
	v_mul_f32_e32 v160, v160, v12
	v_mul_f32_e32 v161, v161, v13
	v_mul_f32_e32 v162, v162, v14
	v_mul_f32_e32 v163, v163, v15
	v_mul_f32_e32 v164, v164, v16
	v_mul_f32_e32 v165, v165, v17
	v_mul_f32_e32 v166, v166, v18
	v_mul_f32_e32 v167, v167, v19
	v_mul_f32_e32 v168, v168, v20
	v_mul_f32_e32 v169, v169, v21
	v_mul_f32_e32 v170, v170, v22
	v_mul_f32_e32 v171, v171, v23
	v_add_f32_e32 v88, 1.0, v136
	v_add_f32_e32 v89, 1.0, v137
	v_add_f32_e32 v90, 1.0, v138
	v_add_f32_e32 v91, 1.0, v139
	v_add_f32_e32 v92, 1.0, v140
	v_add_f32_e32 v93, 1.0, v141
	v_add_f32_e32 v94, 1.0, v142
	v_add_f32_e32 v95, 1.0, v143
	v_add_f32_e32 v96, 1.0, v144
	v_add_f32_e32 v97, 1.0, v145
	v_add_f32_e32 v98, 1.0, v146
	v_add_f32_e32 v99, 1.0, v147
	v_add_f32_e32 v100, 1.0, v148
	v_add_f32_e32 v101, 1.0, v149
	v_add_f32_e32 v102, 1.0, v150
	v_add_f32_e32 v103, 1.0, v151
	v_fma_f32 v156, v156, v88, v120
	v_fma_f32 v157, v157, v89, v121
	v_fma_f32 v158, v158, v90, v122
	v_fma_f32 v159, v159, v91, v123
	v_fma_f32 v160, v160, v92, v124
	v_fma_f32 v161, v161, v93, v125
	v_fma_f32 v162, v162, v94, v126
	v_fma_f32 v163, v163, v95, v127
	v_fma_f32 v164, v164, v96, v128
	v_fma_f32 v165, v165, v97, v129
	v_fma_f32 v166, v166, v98, v130
	v_fma_f32 v167, v167, v99, v131
	v_fma_f32 v168, v168, v100, v132
	v_fma_f32 v169, v169, v101, v133
	v_fma_f32 v170, v170, v102, v134
	v_fma_f32 v171, v171, v103, v135
	v_cvt_pk_bf16_f32 v156, v156, v157
	v_cvt_pk_bf16_f32 v157, v158, v159
	v_cvt_pk_bf16_f32 v158, v160, v161
	v_cvt_pk_bf16_f32 v159, v162, v163
	v_cvt_pk_bf16_f32 v160, v164, v165
	v_cvt_pk_bf16_f32 v161, v166, v167
	v_cvt_pk_bf16_f32 v162, v168, v169
	v_cvt_pk_bf16_f32 v163, v170, v171
	global_store_dwordx4 v5, v[156:159], s[22:23]
	global_store_dwordx4 v5, v[160:163], s[22:23] offset:1024
	v_mul_f32_e32 v152, v104, v104
	v_fmac_f32_e32 v152, v105, v105
	v_fmac_f32_e32 v152, v106, v106
	v_fmac_f32_e32 v152, v107, v107
	v_fmac_f32_e32 v152, v108, v108
	v_fmac_f32_e32 v152, v109, v109
	v_fmac_f32_e32 v152, v110, v110
	v_fmac_f32_e32 v152, v111, v111
	v_fmac_f32_e32 v152, v112, v112
	v_fmac_f32_e32 v152, v113, v113
	v_fmac_f32_e32 v152, v114, v114
	v_fmac_f32_e32 v152, v115, v115
	v_fmac_f32_e32 v152, v116, v116
	v_fmac_f32_e32 v152, v117, v117
	v_fmac_f32_e32 v152, v118, v118
	v_fmac_f32_e32 v152, v119, v119
	v_mov_b32_e32 v153, v152
	s_nop 1
	v_permlane32_swap_b32_e32 v152, v153
	v_add_f32_e32 v152, v152, v153
	v_mov_b32_e32 v153, v152
	s_nop 1
	v_permlane16_swap_b32_e32 v152, v153
	v_add_f32_e32 v152, v152, v153
	s_nop 1
	v_mov_b32_dpp v153, v152 row_ror:8 row_mask:0xf bank_mask:0xf
	v_add_f32_e32 v152, v152, v153
	s_nop 1
	v_mov_b32_dpp v153, v152 row_ror:4 row_mask:0xf bank_mask:0xf
	v_add_f32_e32 v152, v152, v153
	s_nop 1
	v_mov_b32_dpp v153, v152 row_ror:2 row_mask:0xf bank_mask:0xf
	v_add_f32_e32 v152, v152, v153
	s_nop 1
	v_mov_b32_dpp v153, v152 row_ror:1 row_mask:0xf bank_mask:0xf
	v_add_f32_e32 v152, v152, v153
	v_mov_b32_e32 v153, 0x358637bd
	v_fmac_f32_e32 v153, 0x3a800000, v152
	v_rsq_f32_e32 v153, v153
	s_nop 0
	v_mul_f32_e32 v156, v104, v153
	v_mul_f32_e32 v157, v105, v153
	v_mul_f32_e32 v158, v106, v153
	v_mul_f32_e32 v159, v107, v153
	v_mul_f32_e32 v160, v108, v153
	v_mul_f32_e32 v161, v109, v153
	v_mul_f32_e32 v162, v110, v153
	v_mul_f32_e32 v163, v111, v153
	v_mul_f32_e32 v164, v112, v153
	v_mul_f32_e32 v165, v113, v153
	v_mul_f32_e32 v166, v114, v153
	v_mul_f32_e32 v167, v115, v153
	v_mul_f32_e32 v168, v116, v153
	v_mul_f32_e32 v169, v117, v153
	v_mul_f32_e32 v170, v118, v153
	v_mul_f32_e32 v171, v119, v153
	v_mul_f32_e32 v156, v156, v8
	v_mul_f32_e32 v157, v157, v9
	v_mul_f32_e32 v158, v158, v10
	v_mul_f32_e32 v159, v159, v11
	v_mul_f32_e32 v160, v160, v12
	v_mul_f32_e32 v161, v161, v13
	v_mul_f32_e32 v162, v162, v14
	v_mul_f32_e32 v163, v163, v15
	v_mul_f32_e32 v164, v164, v16
	v_mul_f32_e32 v165, v165, v17
	v_mul_f32_e32 v166, v166, v18
	v_mul_f32_e32 v167, v167, v19
	v_mul_f32_e32 v168, v168, v20
	v_mul_f32_e32 v169, v169, v21
	v_mul_f32_e32 v170, v170, v22
	v_mul_f32_e32 v171, v171, v23
	v_add_f32_e32 v104, 1.0, v136
	v_add_f32_e32 v105, 1.0, v137
	v_add_f32_e32 v106, 1.0, v138
	v_add_f32_e32 v107, 1.0, v139
	v_add_f32_e32 v108, 1.0, v140
	v_add_f32_e32 v109, 1.0, v141
	v_add_f32_e32 v110, 1.0, v142
	v_add_f32_e32 v111, 1.0, v143
	v_add_f32_e32 v112, 1.0, v144
	v_add_f32_e32 v113, 1.0, v145
	v_add_f32_e32 v114, 1.0, v146
	v_add_f32_e32 v115, 1.0, v147
	v_add_f32_e32 v116, 1.0, v148
	v_add_f32_e32 v117, 1.0, v149
	v_add_f32_e32 v118, 1.0, v150
	v_add_f32_e32 v119, 1.0, v151
	v_fma_f32 v156, v156, v104, v120
	v_fma_f32 v157, v157, v105, v121
	v_fma_f32 v158, v158, v106, v122
	v_fma_f32 v159, v159, v107, v123
	v_fma_f32 v160, v160, v108, v124
	v_fma_f32 v161, v161, v109, v125
	v_fma_f32 v162, v162, v110, v126
	v_fma_f32 v163, v163, v111, v127
	v_fma_f32 v164, v164, v112, v128
	v_fma_f32 v165, v165, v113, v129
	v_fma_f32 v166, v166, v114, v130
	v_fma_f32 v167, v167, v115, v131
	v_fma_f32 v168, v168, v116, v132
	v_fma_f32 v169, v169, v117, v133
	v_fma_f32 v170, v170, v118, v134
	v_fma_f32 v171, v171, v119, v135
	v_cvt_pk_bf16_f32 v156, v156, v157
	v_cvt_pk_bf16_f32 v157, v158, v159
	v_cvt_pk_bf16_f32 v158, v160, v161
	v_cvt_pk_bf16_f32 v159, v162, v163
	v_cvt_pk_bf16_f32 v160, v164, v165
	v_cvt_pk_bf16_f32 v161, v166, v167
	v_cvt_pk_bf16_f32 v162, v168, v169
	v_cvt_pk_bf16_f32 v163, v170, v171
	global_store_dwordx4 v5, v[156:159], s[28:29]
	global_store_dwordx4 v5, v[160:163], s[28:29] offset:1024
	s_add_u32 s22, s22, 0x800000
	s_addc_u32 s23, s23, 0
	s_add_u32 s28, s28, 0x800000
	s_addc_u32 s29, s29, 0
	global_load_dwordx4 v[88:91], v4, s[18:19] nt
	global_load_dwordx4 v[92:95], v4, s[18:19] offset:16 nt
	global_load_dwordx4 v[96:99], v4, s[18:19] offset:2048 nt
	global_load_dwordx4 v[100:103], v4, s[18:19] offset:2064 nt
	global_load_dwordx4 v[104:107], v4, s[26:27] nt
	global_load_dwordx4 v[108:111], v4, s[26:27] offset:16 nt
	global_load_dwordx4 v[112:115], v4, s[26:27] offset:2048 nt
	global_load_dwordx4 v[116:119], v4, s[26:27] offset:2064 nt
	global_load_dwordx4 v[120:123], v4, s[20:21]
	global_load_dwordx4 v[124:127], v4, s[20:21] offset:16
	global_load_dwordx4 v[128:131], v4, s[20:21] offset:2048
	global_load_dwordx4 v[132:135], v4, s[20:21] offset:2064
	global_load_dwordx4 v[136:139], v4, s[12:13]
	global_load_dwordx4 v[140:143], v4, s[12:13] offset:16
	global_load_dwordx4 v[144:147], v4, s[12:13] offset:2048
	global_load_dwordx4 v[148:151], v4, s[12:13] offset:2064
	s_add_u32 s18, s18, 0x1000000
	s_addc_u32 s19, s19, 0
	s_add_u32 s26, s26, 0x1000000
	s_addc_u32 s27, s27, 0
	s_add_u32 s20, s20, 0x6000
	s_addc_u32 s21, s21, 0
	s_add_u32 s12, s12, 0x6000
	s_addc_u32 s13, s13, 0
	s_waitcnt vmcnt(20)
	v_mul_f32_e32 v152, v24, v24
	v_fmac_f32_e32 v152, v25, v25
	v_fmac_f32_e32 v152, v26, v26
	v_fmac_f32_e32 v152, v27, v27
	v_fmac_f32_e32 v152, v28, v28
	v_fmac_f32_e32 v152, v29, v29
	v_fmac_f32_e32 v152, v30, v30
	v_fmac_f32_e32 v152, v31, v31
	v_fmac_f32_e32 v152, v32, v32
	v_fmac_f32_e32 v152, v33, v33
	v_fmac_f32_e32 v152, v34, v34
	v_fmac_f32_e32 v152, v35, v35
	v_fmac_f32_e32 v152, v36, v36
	v_fmac_f32_e32 v152, v37, v37
	v_fmac_f32_e32 v152, v38, v38
	v_fmac_f32_e32 v152, v39, v39
	v_mov_b32_e32 v153, v152
	s_nop 1
	v_permlane32_swap_b32_e32 v152, v153
	v_add_f32_e32 v152, v152, v153
	v_mov_b32_e32 v153, v152
	s_nop 1
	v_permlane16_swap_b32_e32 v152, v153
	v_add_f32_e32 v152, v152, v153
	s_nop 1
	v_mov_b32_dpp v153, v152 row_ror:8 row_mask:0xf bank_mask:0xf
	v_add_f32_e32 v152, v152, v153
	s_nop 1
	v_mov_b32_dpp v153, v152 row_ror:4 row_mask:0xf bank_mask:0xf
	v_add_f32_e32 v152, v152, v153
	s_nop 1
	v_mov_b32_dpp v153, v152 row_ror:2 row_mask:0xf bank_mask:0xf
	v_add_f32_e32 v152, v152, v153
	s_nop 1
	v_mov_b32_dpp v153, v152 row_ror:1 row_mask:0xf bank_mask:0xf
	v_add_f32_e32 v152, v152, v153
	v_mov_b32_e32 v153, 0x358637bd
	v_fmac_f32_e32 v153, 0x3a800000, v152
	v_rsq_f32_e32 v153, v153
	s_nop 0
	v_mul_f32_e32 v156, v24, v153
	v_mul_f32_e32 v157, v25, v153
	v_mul_f32_e32 v158, v26, v153
	v_mul_f32_e32 v159, v27, v153
	v_mul_f32_e32 v160, v28, v153
	v_mul_f32_e32 v161, v29, v153
	v_mul_f32_e32 v162, v30, v153
	v_mul_f32_e32 v163, v31, v153
	v_mul_f32_e32 v164, v32, v153
	v_mul_f32_e32 v165, v33, v153
	v_mul_f32_e32 v166, v34, v153
	v_mul_f32_e32 v167, v35, v153
	v_mul_f32_e32 v168, v36, v153
	v_mul_f32_e32 v169, v37, v153
	v_mul_f32_e32 v170, v38, v153
	v_mul_f32_e32 v171, v39, v153
	v_mul_f32_e32 v156, v156, v8
	v_mul_f32_e32 v157, v157, v9
	v_mul_f32_e32 v158, v158, v10
	v_mul_f32_e32 v159, v159, v11
	v_mul_f32_e32 v160, v160, v12
	v_mul_f32_e32 v161, v161, v13
	v_mul_f32_e32 v162, v162, v14
	v_mul_f32_e32 v163, v163, v15
	v_mul_f32_e32 v164, v164, v16
	v_mul_f32_e32 v165, v165, v17
	v_mul_f32_e32 v166, v166, v18
	v_mul_f32_e32 v167, v167, v19
	v_mul_f32_e32 v168, v168, v20
	v_mul_f32_e32 v169, v169, v21
	v_mul_f32_e32 v170, v170, v22
	v_mul_f32_e32 v171, v171, v23
	v_add_f32_e32 v24, 1.0, v72
	v_add_f32_e32 v25, 1.0, v73
	v_add_f32_e32 v26, 1.0, v74
	v_add_f32_e32 v27, 1.0, v75
	v_add_f32_e32 v28, 1.0, v76
	v_add_f32_e32 v29, 1.0, v77
	v_add_f32_e32 v30, 1.0, v78
	v_add_f32_e32 v31, 1.0, v79
	v_add_f32_e32 v32, 1.0, v80
	v_add_f32_e32 v33, 1.0, v81
	v_add_f32_e32 v34, 1.0, v82
	v_add_f32_e32 v35, 1.0, v83
	v_add_f32_e32 v36, 1.0, v84
	v_add_f32_e32 v37, 1.0, v85
	v_add_f32_e32 v38, 1.0, v86
	v_add_f32_e32 v39, 1.0, v87
	v_fma_f32 v156, v156, v24, v56
	v_fma_f32 v157, v157, v25, v57
	v_fma_f32 v158, v158, v26, v58
	v_fma_f32 v159, v159, v27, v59
	v_fma_f32 v160, v160, v28, v60
	v_fma_f32 v161, v161, v29, v61
	v_fma_f32 v162, v162, v30, v62
	v_fma_f32 v163, v163, v31, v63
	v_fma_f32 v164, v164, v32, v64
	v_fma_f32 v165, v165, v33, v65
	v_fma_f32 v166, v166, v34, v66
	v_fma_f32 v167, v167, v35, v67
	v_fma_f32 v168, v168, v36, v68
	v_fma_f32 v169, v169, v37, v69
	v_fma_f32 v170, v170, v38, v70
	v_fma_f32 v171, v171, v39, v71
	v_cvt_pk_bf16_f32 v156, v156, v157
	v_cvt_pk_bf16_f32 v157, v158, v159
	v_cvt_pk_bf16_f32 v158, v160, v161
	v_cvt_pk_bf16_f32 v159, v162, v163
	v_cvt_pk_bf16_f32 v160, v164, v165
	v_cvt_pk_bf16_f32 v161, v166, v167
	v_cvt_pk_bf16_f32 v162, v168, v169
	v_cvt_pk_bf16_f32 v163, v170, v171
	global_store_dwordx4 v5, v[156:159], s[22:23]
	global_store_dwordx4 v5, v[160:163], s[22:23] offset:1024
	v_mul_f32_e32 v152, v40, v40
	v_fmac_f32_e32 v152, v41, v41
	v_fmac_f32_e32 v152, v42, v42
	v_fmac_f32_e32 v152, v43, v43
	v_fmac_f32_e32 v152, v44, v44
	v_fmac_f32_e32 v152, v45, v45
	v_fmac_f32_e32 v152, v46, v46
	v_fmac_f32_e32 v152, v47, v47
	v_fmac_f32_e32 v152, v48, v48
	v_fmac_f32_e32 v152, v49, v49
	v_fmac_f32_e32 v152, v50, v50
	v_fmac_f32_e32 v152, v51, v51
	v_fmac_f32_e32 v152, v52, v52
	v_fmac_f32_e32 v152, v53, v53
	v_fmac_f32_e32 v152, v54, v54
	v_fmac_f32_e32 v152, v55, v55
	v_mov_b32_e32 v153, v152
	s_nop 1
	v_permlane32_swap_b32_e32 v152, v153
	v_add_f32_e32 v152, v152, v153
	v_mov_b32_e32 v153, v152
	s_nop 1
	v_permlane16_swap_b32_e32 v152, v153
	v_add_f32_e32 v152, v152, v153
	s_nop 1
	v_mov_b32_dpp v153, v152 row_ror:8 row_mask:0xf bank_mask:0xf
	v_add_f32_e32 v152, v152, v153
	s_nop 1
	v_mov_b32_dpp v153, v152 row_ror:4 row_mask:0xf bank_mask:0xf
	v_add_f32_e32 v152, v152, v153
	s_nop 1
	v_mov_b32_dpp v153, v152 row_ror:2 row_mask:0xf bank_mask:0xf
	v_add_f32_e32 v152, v152, v153
	s_nop 1
	v_mov_b32_dpp v153, v152 row_ror:1 row_mask:0xf bank_mask:0xf
	v_add_f32_e32 v152, v152, v153
	v_mov_b32_e32 v153, 0x358637bd
	v_fmac_f32_e32 v153, 0x3a800000, v152
	v_rsq_f32_e32 v153, v153
	s_nop 0
	v_mul_f32_e32 v156, v40, v153
	v_mul_f32_e32 v157, v41, v153
	v_mul_f32_e32 v158, v42, v153
	v_mul_f32_e32 v159, v43, v153
	v_mul_f32_e32 v160, v44, v153
	v_mul_f32_e32 v161, v45, v153
	v_mul_f32_e32 v162, v46, v153
	v_mul_f32_e32 v163, v47, v153
	v_mul_f32_e32 v164, v48, v153
	v_mul_f32_e32 v165, v49, v153
	v_mul_f32_e32 v166, v50, v153
	v_mul_f32_e32 v167, v51, v153
	v_mul_f32_e32 v168, v52, v153
	v_mul_f32_e32 v169, v53, v153
	v_mul_f32_e32 v170, v54, v153
	v_mul_f32_e32 v171, v55, v153
	v_mul_f32_e32 v156, v156, v8
	v_mul_f32_e32 v157, v157, v9
	v_mul_f32_e32 v158, v158, v10
	v_mul_f32_e32 v159, v159, v11
	v_mul_f32_e32 v160, v160, v12
	v_mul_f32_e32 v161, v161, v13
	v_mul_f32_e32 v162, v162, v14
	v_mul_f32_e32 v163, v163, v15
	v_mul_f32_e32 v164, v164, v16
	v_mul_f32_e32 v165, v165, v17
	v_mul_f32_e32 v166, v166, v18
	v_mul_f32_e32 v167, v167, v19
	v_mul_f32_e32 v168, v168, v20
	v_mul_f32_e32 v169, v169, v21
	v_mul_f32_e32 v170, v170, v22
	v_mul_f32_e32 v171, v171, v23
	v_add_f32_e32 v40, 1.0, v72
	v_add_f32_e32 v41, 1.0, v73
	v_add_f32_e32 v42, 1.0, v74
	v_add_f32_e32 v43, 1.0, v75
	v_add_f32_e32 v44, 1.0, v76
	v_add_f32_e32 v45, 1.0, v77
	v_add_f32_e32 v46, 1.0, v78
	v_add_f32_e32 v47, 1.0, v79
	v_add_f32_e32 v48, 1.0, v80
	v_add_f32_e32 v49, 1.0, v81
	v_add_f32_e32 v50, 1.0, v82
	v_add_f32_e32 v51, 1.0, v83
	v_add_f32_e32 v52, 1.0, v84
	v_add_f32_e32 v53, 1.0, v85
	v_add_f32_e32 v54, 1.0, v86
	v_add_f32_e32 v55, 1.0, v87
	v_fma_f32 v156, v156, v40, v56
	v_fma_f32 v157, v157, v41, v57
	v_fma_f32 v158, v158, v42, v58
	v_fma_f32 v159, v159, v43, v59
	v_fma_f32 v160, v160, v44, v60
	v_fma_f32 v161, v161, v45, v61
	v_fma_f32 v162, v162, v46, v62
	v_fma_f32 v163, v163, v47, v63
	v_fma_f32 v164, v164, v48, v64
	v_fma_f32 v165, v165, v49, v65
	v_fma_f32 v166, v166, v50, v66
	v_fma_f32 v167, v167, v51, v67
	v_fma_f32 v168, v168, v52, v68
	v_fma_f32 v169, v169, v53, v69
	v_fma_f32 v170, v170, v54, v70
	v_fma_f32 v171, v171, v55, v71
	v_cvt_pk_bf16_f32 v156, v156, v157
	v_cvt_pk_bf16_f32 v157, v158, v159
	v_cvt_pk_bf16_f32 v158, v160, v161
	v_cvt_pk_bf16_f32 v159, v162, v163
	v_cvt_pk_bf16_f32 v160, v164, v165
	v_cvt_pk_bf16_f32 v161, v166, v167
	v_cvt_pk_bf16_f32 v162, v168, v169
	v_cvt_pk_bf16_f32 v163, v170, v171
	global_store_dwordx4 v5, v[156:159], s[28:29]
	global_store_dwordx4 v5, v[160:163], s[28:29] offset:1024
	s_add_u32 s22, s22, 0x800000
	s_addc_u32 s23, s23, 0
	s_add_u32 s28, s28, 0x800000
	s_addc_u32 s29, s29, 0
	global_load_dwordx4 v[24:27], v4, s[18:19] nt
	global_load_dwordx4 v[28:31], v4, s[18:19] offset:16 nt
	global_load_dwordx4 v[32:35], v4, s[18:19] offset:2048 nt
	global_load_dwordx4 v[36:39], v4, s[18:19] offset:2064 nt
	global_load_dwordx4 v[40:43], v4, s[26:27] nt
	global_load_dwordx4 v[44:47], v4, s[26:27] offset:16 nt
	global_load_dwordx4 v[48:51], v4, s[26:27] offset:2048 nt
	global_load_dwordx4 v[52:55], v4, s[26:27] offset:2064 nt
	global_load_dwordx4 v[56:59], v4, s[20:21]
	global_load_dwordx4 v[60:63], v4, s[20:21] offset:16
	global_load_dwordx4 v[64:67], v4, s[20:21] offset:2048
	global_load_dwordx4 v[68:71], v4, s[20:21] offset:2064
	global_load_dwordx4 v[72:75], v4, s[12:13]
	global_load_dwordx4 v[76:79], v4, s[12:13] offset:16
	global_load_dwordx4 v[80:83], v4, s[12:13] offset:2048
	global_load_dwordx4 v[84:87], v4, s[12:13] offset:2064
	s_add_u32 s18, s18, 0x1000000
	s_addc_u32 s19, s19, 0
	s_add_u32 s26, s26, 0x1000000
	s_addc_u32 s27, s27, 0
	s_add_u32 s20, s20, 0x6000
	s_addc_u32 s21, s21, 0
	s_add_u32 s12, s12, 0x6000
	s_addc_u32 s13, s13, 0
	s_waitcnt vmcnt(20)
	v_mul_f32_e32 v152, v88, v88
	v_fmac_f32_e32 v152, v89, v89
	v_fmac_f32_e32 v152, v90, v90
	v_fmac_f32_e32 v152, v91, v91
	v_fmac_f32_e32 v152, v92, v92
	v_fmac_f32_e32 v152, v93, v93
	v_fmac_f32_e32 v152, v94, v94
	v_fmac_f32_e32 v152, v95, v95
	v_fmac_f32_e32 v152, v96, v96
	v_fmac_f32_e32 v152, v97, v97
	v_fmac_f32_e32 v152, v98, v98
	v_fmac_f32_e32 v152, v99, v99
	v_fmac_f32_e32 v152, v100, v100
	v_fmac_f32_e32 v152, v101, v101
	v_fmac_f32_e32 v152, v102, v102
	v_fmac_f32_e32 v152, v103, v103
	v_mov_b32_e32 v153, v152
	s_nop 1
	v_permlane32_swap_b32_e32 v152, v153
	v_add_f32_e32 v152, v152, v153
	v_mov_b32_e32 v153, v152
	s_nop 1
	v_permlane16_swap_b32_e32 v152, v153
	v_add_f32_e32 v152, v152, v153
	s_nop 1
	v_mov_b32_dpp v153, v152 row_ror:8 row_mask:0xf bank_mask:0xf
	v_add_f32_e32 v152, v152, v153
	s_nop 1
	v_mov_b32_dpp v153, v152 row_ror:4 row_mask:0xf bank_mask:0xf
	v_add_f32_e32 v152, v152, v153
	s_nop 1
	v_mov_b32_dpp v153, v152 row_ror:2 row_mask:0xf bank_mask:0xf
	v_add_f32_e32 v152, v152, v153
	s_nop 1
	v_mov_b32_dpp v153, v152 row_ror:1 row_mask:0xf bank_mask:0xf
	v_add_f32_e32 v152, v152, v153
	v_mov_b32_e32 v153, 0x358637bd
	v_fmac_f32_e32 v153, 0x3a800000, v152
	v_rsq_f32_e32 v153, v153
	s_nop 0
	v_mul_f32_e32 v156, v88, v153
	v_mul_f32_e32 v157, v89, v153
	v_mul_f32_e32 v158, v90, v153
	v_mul_f32_e32 v159, v91, v153
	v_mul_f32_e32 v160, v92, v153
	v_mul_f32_e32 v161, v93, v153
	v_mul_f32_e32 v162, v94, v153
	v_mul_f32_e32 v163, v95, v153
	v_mul_f32_e32 v164, v96, v153
	v_mul_f32_e32 v165, v97, v153
	v_mul_f32_e32 v166, v98, v153
	v_mul_f32_e32 v167, v99, v153
	v_mul_f32_e32 v168, v100, v153
	v_mul_f32_e32 v169, v101, v153
	v_mul_f32_e32 v170, v102, v153
	v_mul_f32_e32 v171, v103, v153
	v_mul_f32_e32 v156, v156, v8
	v_mul_f32_e32 v157, v157, v9
	v_mul_f32_e32 v158, v158, v10
	v_mul_f32_e32 v159, v159, v11
	v_mul_f32_e32 v160, v160, v12
	v_mul_f32_e32 v161, v161, v13
	v_mul_f32_e32 v162, v162, v14
	v_mul_f32_e32 v163, v163, v15
	v_mul_f32_e32 v164, v164, v16
	v_mul_f32_e32 v165, v165, v17
	v_mul_f32_e32 v166, v166, v18
	v_mul_f32_e32 v167, v167, v19
	v_mul_f32_e32 v168, v168, v20
	v_mul_f32_e32 v169, v169, v21
	v_mul_f32_e32 v170, v170, v22
	v_mul_f32_e32 v171, v171, v23
	v_add_f32_e32 v88, 1.0, v136
	v_add_f32_e32 v89, 1.0, v137
	v_add_f32_e32 v90, 1.0, v138
	v_add_f32_e32 v91, 1.0, v139
	v_add_f32_e32 v92, 1.0, v140
	v_add_f32_e32 v93, 1.0, v141
	v_add_f32_e32 v94, 1.0, v142
	v_add_f32_e32 v95, 1.0, v143
	v_add_f32_e32 v96, 1.0, v144
	v_add_f32_e32 v97, 1.0, v145
	v_add_f32_e32 v98, 1.0, v146
	v_add_f32_e32 v99, 1.0, v147
	v_add_f32_e32 v100, 1.0, v148
	v_add_f32_e32 v101, 1.0, v149
	v_add_f32_e32 v102, 1.0, v150
	v_add_f32_e32 v103, 1.0, v151
	v_fma_f32 v156, v156, v88, v120
	v_fma_f32 v157, v157, v89, v121
	v_fma_f32 v158, v158, v90, v122
	v_fma_f32 v159, v159, v91, v123
	v_fma_f32 v160, v160, v92, v124
	v_fma_f32 v161, v161, v93, v125
	v_fma_f32 v162, v162, v94, v126
	v_fma_f32 v163, v163, v95, v127
	v_fma_f32 v164, v164, v96, v128
	v_fma_f32 v165, v165, v97, v129
	v_fma_f32 v166, v166, v98, v130
	v_fma_f32 v167, v167, v99, v131
	v_fma_f32 v168, v168, v100, v132
	v_fma_f32 v169, v169, v101, v133
	v_fma_f32 v170, v170, v102, v134
	v_fma_f32 v171, v171, v103, v135
	v_cvt_pk_bf16_f32 v156, v156, v157
	v_cvt_pk_bf16_f32 v157, v158, v159
	v_cvt_pk_bf16_f32 v158, v160, v161
	v_cvt_pk_bf16_f32 v159, v162, v163
	v_cvt_pk_bf16_f32 v160, v164, v165
	v_cvt_pk_bf16_f32 v161, v166, v167
	v_cvt_pk_bf16_f32 v162, v168, v169
	v_cvt_pk_bf16_f32 v163, v170, v171
	global_store_dwordx4 v5, v[156:159], s[22:23]
	global_store_dwordx4 v5, v[160:163], s[22:23] offset:1024
	v_mul_f32_e32 v152, v104, v104
	v_fmac_f32_e32 v152, v105, v105
	v_fmac_f32_e32 v152, v106, v106
	v_fmac_f32_e32 v152, v107, v107
	v_fmac_f32_e32 v152, v108, v108
	v_fmac_f32_e32 v152, v109, v109
	v_fmac_f32_e32 v152, v110, v110
	v_fmac_f32_e32 v152, v111, v111
	v_fmac_f32_e32 v152, v112, v112
	v_fmac_f32_e32 v152, v113, v113
	v_fmac_f32_e32 v152, v114, v114
	v_fmac_f32_e32 v152, v115, v115
	v_fmac_f32_e32 v152, v116, v116
	v_fmac_f32_e32 v152, v117, v117
	v_fmac_f32_e32 v152, v118, v118
	v_fmac_f32_e32 v152, v119, v119
	v_mov_b32_e32 v153, v152
	s_nop 1
	v_permlane32_swap_b32_e32 v152, v153
	v_add_f32_e32 v152, v152, v153
	v_mov_b32_e32 v153, v152
	s_nop 1
	v_permlane16_swap_b32_e32 v152, v153
	v_add_f32_e32 v152, v152, v153
	s_nop 1
	v_mov_b32_dpp v153, v152 row_ror:8 row_mask:0xf bank_mask:0xf
	v_add_f32_e32 v152, v152, v153
	s_nop 1
	v_mov_b32_dpp v153, v152 row_ror:4 row_mask:0xf bank_mask:0xf
	v_add_f32_e32 v152, v152, v153
	s_nop 1
	v_mov_b32_dpp v153, v152 row_ror:2 row_mask:0xf bank_mask:0xf
	v_add_f32_e32 v152, v152, v153
	s_nop 1
	v_mov_b32_dpp v153, v152 row_ror:1 row_mask:0xf bank_mask:0xf
	v_add_f32_e32 v152, v152, v153
	v_mov_b32_e32 v153, 0x358637bd
	v_fmac_f32_e32 v153, 0x3a800000, v152
	v_rsq_f32_e32 v153, v153
	s_nop 0
	v_mul_f32_e32 v156, v104, v153
	v_mul_f32_e32 v157, v105, v153
	v_mul_f32_e32 v158, v106, v153
	v_mul_f32_e32 v159, v107, v153
	v_mul_f32_e32 v160, v108, v153
	v_mul_f32_e32 v161, v109, v153
	v_mul_f32_e32 v162, v110, v153
	v_mul_f32_e32 v163, v111, v153
	v_mul_f32_e32 v164, v112, v153
	v_mul_f32_e32 v165, v113, v153
	v_mul_f32_e32 v166, v114, v153
	v_mul_f32_e32 v167, v115, v153
	v_mul_f32_e32 v168, v116, v153
	v_mul_f32_e32 v169, v117, v153
	v_mul_f32_e32 v170, v118, v153
	v_mul_f32_e32 v171, v119, v153
	v_mul_f32_e32 v156, v156, v8
	v_mul_f32_e32 v157, v157, v9
	v_mul_f32_e32 v158, v158, v10
	v_mul_f32_e32 v159, v159, v11
	v_mul_f32_e32 v160, v160, v12
	v_mul_f32_e32 v161, v161, v13
	v_mul_f32_e32 v162, v162, v14
	v_mul_f32_e32 v163, v163, v15
	v_mul_f32_e32 v164, v164, v16
	v_mul_f32_e32 v165, v165, v17
	v_mul_f32_e32 v166, v166, v18
	v_mul_f32_e32 v167, v167, v19
	v_mul_f32_e32 v168, v168, v20
	v_mul_f32_e32 v169, v169, v21
	v_mul_f32_e32 v170, v170, v22
	v_mul_f32_e32 v171, v171, v23
	v_add_f32_e32 v104, 1.0, v136
	v_add_f32_e32 v105, 1.0, v137
	v_add_f32_e32 v106, 1.0, v138
	v_add_f32_e32 v107, 1.0, v139
	v_add_f32_e32 v108, 1.0, v140
	v_add_f32_e32 v109, 1.0, v141
	v_add_f32_e32 v110, 1.0, v142
	v_add_f32_e32 v111, 1.0, v143
	v_add_f32_e32 v112, 1.0, v144
	v_add_f32_e32 v113, 1.0, v145
	v_add_f32_e32 v114, 1.0, v146
	v_add_f32_e32 v115, 1.0, v147
	v_add_f32_e32 v116, 1.0, v148
	v_add_f32_e32 v117, 1.0, v149
	v_add_f32_e32 v118, 1.0, v150
	v_add_f32_e32 v119, 1.0, v151
	v_fma_f32 v156, v156, v104, v120
	v_fma_f32 v157, v157, v105, v121
	v_fma_f32 v158, v158, v106, v122
	v_fma_f32 v159, v159, v107, v123
	v_fma_f32 v160, v160, v108, v124
	v_fma_f32 v161, v161, v109, v125
	v_fma_f32 v162, v162, v110, v126
	v_fma_f32 v163, v163, v111, v127
	v_fma_f32 v164, v164, v112, v128
	v_fma_f32 v165, v165, v113, v129
	v_fma_f32 v166, v166, v114, v130
	v_fma_f32 v167, v167, v115, v131
	v_fma_f32 v168, v168, v116, v132
	v_fma_f32 v169, v169, v117, v133
	v_fma_f32 v170, v170, v118, v134
	v_fma_f32 v171, v171, v119, v135
	v_cvt_pk_bf16_f32 v156, v156, v157
	v_cvt_pk_bf16_f32 v157, v158, v159
	v_cvt_pk_bf16_f32 v158, v160, v161
	v_cvt_pk_bf16_f32 v159, v162, v163
	v_cvt_pk_bf16_f32 v160, v164, v165
	v_cvt_pk_bf16_f32 v161, v166, v167
	v_cvt_pk_bf16_f32 v162, v168, v169
	v_cvt_pk_bf16_f32 v163, v170, v171
	global_store_dwordx4 v5, v[156:159], s[28:29]
	global_store_dwordx4 v5, v[160:163], s[28:29] offset:1024
	s_add_u32 s22, s22, 0x800000
	s_addc_u32 s23, s23, 0
	s_add_u32 s28, s28, 0x800000
	s_addc_u32 s29, s29, 0
	global_load_dwordx4 v[88:91], v4, s[18:19] nt
	global_load_dwordx4 v[92:95], v4, s[18:19] offset:16 nt
	global_load_dwordx4 v[96:99], v4, s[18:19] offset:2048 nt
	global_load_dwordx4 v[100:103], v4, s[18:19] offset:2064 nt
	global_load_dwordx4 v[104:107], v4, s[26:27] nt
	global_load_dwordx4 v[108:111], v4, s[26:27] offset:16 nt
	global_load_dwordx4 v[112:115], v4, s[26:27] offset:2048 nt
	global_load_dwordx4 v[116:119], v4, s[26:27] offset:2064 nt
	global_load_dwordx4 v[120:123], v4, s[20:21]
	global_load_dwordx4 v[124:127], v4, s[20:21] offset:16
	global_load_dwordx4 v[128:131], v4, s[20:21] offset:2048
	global_load_dwordx4 v[132:135], v4, s[20:21] offset:2064
	global_load_dwordx4 v[136:139], v4, s[12:13]
	global_load_dwordx4 v[140:143], v4, s[12:13] offset:16
	global_load_dwordx4 v[144:147], v4, s[12:13] offset:2048
	global_load_dwordx4 v[148:151], v4, s[12:13] offset:2064
	s_add_u32 s18, s18, 0x1000000
	s_addc_u32 s19, s19, 0
	s_add_u32 s26, s26, 0x1000000
	s_addc_u32 s27, s27, 0
	s_add_u32 s20, s20, 0x6000
	s_addc_u32 s21, s21, 0
	s_add_u32 s12, s12, 0x6000
	s_addc_u32 s13, s13, 0
	s_waitcnt vmcnt(20)
	v_mul_f32_e32 v152, v24, v24
	v_fmac_f32_e32 v152, v25, v25
	v_fmac_f32_e32 v152, v26, v26
	v_fmac_f32_e32 v152, v27, v27
	v_fmac_f32_e32 v152, v28, v28
	v_fmac_f32_e32 v152, v29, v29
	v_fmac_f32_e32 v152, v30, v30
	v_fmac_f32_e32 v152, v31, v31
	v_fmac_f32_e32 v152, v32, v32
	v_fmac_f32_e32 v152, v33, v33
	v_fmac_f32_e32 v152, v34, v34
	v_fmac_f32_e32 v152, v35, v35
	v_fmac_f32_e32 v152, v36, v36
	v_fmac_f32_e32 v152, v37, v37
	v_fmac_f32_e32 v152, v38, v38
	v_fmac_f32_e32 v152, v39, v39
	v_mov_b32_e32 v153, v152
	s_nop 1
	v_permlane32_swap_b32_e32 v152, v153
	v_add_f32_e32 v152, v152, v153
	v_mov_b32_e32 v153, v152
	s_nop 1
	v_permlane16_swap_b32_e32 v152, v153
	v_add_f32_e32 v152, v152, v153
	s_nop 1
	v_mov_b32_dpp v153, v152 row_ror:8 row_mask:0xf bank_mask:0xf
	v_add_f32_e32 v152, v152, v153
	s_nop 1
	v_mov_b32_dpp v153, v152 row_ror:4 row_mask:0xf bank_mask:0xf
	v_add_f32_e32 v152, v152, v153
	s_nop 1
	v_mov_b32_dpp v153, v152 row_ror:2 row_mask:0xf bank_mask:0xf
	v_add_f32_e32 v152, v152, v153
	s_nop 1
	v_mov_b32_dpp v153, v152 row_ror:1 row_mask:0xf bank_mask:0xf
	v_add_f32_e32 v152, v152, v153
	v_mov_b32_e32 v153, 0x358637bd
	v_fmac_f32_e32 v153, 0x3a800000, v152
	v_rsq_f32_e32 v153, v153
	s_nop 0
	v_mul_f32_e32 v156, v24, v153
	v_mul_f32_e32 v157, v25, v153
	v_mul_f32_e32 v158, v26, v153
	v_mul_f32_e32 v159, v27, v153
	v_mul_f32_e32 v160, v28, v153
	v_mul_f32_e32 v161, v29, v153
	v_mul_f32_e32 v162, v30, v153
	v_mul_f32_e32 v163, v31, v153
	v_mul_f32_e32 v164, v32, v153
	v_mul_f32_e32 v165, v33, v153
	v_mul_f32_e32 v166, v34, v153
	v_mul_f32_e32 v167, v35, v153
	v_mul_f32_e32 v168, v36, v153
	v_mul_f32_e32 v169, v37, v153
	v_mul_f32_e32 v170, v38, v153
	v_mul_f32_e32 v171, v39, v153
	v_mul_f32_e32 v156, v156, v8
	v_mul_f32_e32 v157, v157, v9
	v_mul_f32_e32 v158, v158, v10
	v_mul_f32_e32 v159, v159, v11
	v_mul_f32_e32 v160, v160, v12
	v_mul_f32_e32 v161, v161, v13
	v_mul_f32_e32 v162, v162, v14
	v_mul_f32_e32 v163, v163, v15
	v_mul_f32_e32 v164, v164, v16
	v_mul_f32_e32 v165, v165, v17
	v_mul_f32_e32 v166, v166, v18
	v_mul_f32_e32 v167, v167, v19
	v_mul_f32_e32 v168, v168, v20
	v_mul_f32_e32 v169, v169, v21
	v_mul_f32_e32 v170, v170, v22
	v_mul_f32_e32 v171, v171, v23
	v_add_f32_e32 v24, 1.0, v72
	v_add_f32_e32 v25, 1.0, v73
	v_add_f32_e32 v26, 1.0, v74
	v_add_f32_e32 v27, 1.0, v75
	v_add_f32_e32 v28, 1.0, v76
	v_add_f32_e32 v29, 1.0, v77
	v_add_f32_e32 v30, 1.0, v78
	v_add_f32_e32 v31, 1.0, v79
	v_add_f32_e32 v32, 1.0, v80
	v_add_f32_e32 v33, 1.0, v81
	v_add_f32_e32 v34, 1.0, v82
	v_add_f32_e32 v35, 1.0, v83
	v_add_f32_e32 v36, 1.0, v84
	v_add_f32_e32 v37, 1.0, v85
	v_add_f32_e32 v38, 1.0, v86
	v_add_f32_e32 v39, 1.0, v87
	v_fma_f32 v156, v156, v24, v56
	v_fma_f32 v157, v157, v25, v57
	v_fma_f32 v158, v158, v26, v58
	v_fma_f32 v159, v159, v27, v59
	v_fma_f32 v160, v160, v28, v60
	v_fma_f32 v161, v161, v29, v61
	v_fma_f32 v162, v162, v30, v62
	v_fma_f32 v163, v163, v31, v63
	v_fma_f32 v164, v164, v32, v64
	v_fma_f32 v165, v165, v33, v65
	v_fma_f32 v166, v166, v34, v66
	v_fma_f32 v167, v167, v35, v67
	v_fma_f32 v168, v168, v36, v68
	v_fma_f32 v169, v169, v37, v69
	v_fma_f32 v170, v170, v38, v70
	v_fma_f32 v171, v171, v39, v71
	v_cvt_pk_bf16_f32 v156, v156, v157
	v_cvt_pk_bf16_f32 v157, v158, v159
	v_cvt_pk_bf16_f32 v158, v160, v161
	v_cvt_pk_bf16_f32 v159, v162, v163
	v_cvt_pk_bf16_f32 v160, v164, v165
	v_cvt_pk_bf16_f32 v161, v166, v167
	v_cvt_pk_bf16_f32 v162, v168, v169
	v_cvt_pk_bf16_f32 v163, v170, v171
	global_store_dwordx4 v5, v[156:159], s[22:23]
	global_store_dwordx4 v5, v[160:163], s[22:23] offset:1024
	v_mul_f32_e32 v152, v40, v40
	v_fmac_f32_e32 v152, v41, v41
	v_fmac_f32_e32 v152, v42, v42
	v_fmac_f32_e32 v152, v43, v43
	v_fmac_f32_e32 v152, v44, v44
	v_fmac_f32_e32 v152, v45, v45
	v_fmac_f32_e32 v152, v46, v46
	v_fmac_f32_e32 v152, v47, v47
	v_fmac_f32_e32 v152, v48, v48
	v_fmac_f32_e32 v152, v49, v49
	v_fmac_f32_e32 v152, v50, v50
	v_fmac_f32_e32 v152, v51, v51
	v_fmac_f32_e32 v152, v52, v52
	v_fmac_f32_e32 v152, v53, v53
	v_fmac_f32_e32 v152, v54, v54
	v_fmac_f32_e32 v152, v55, v55
	v_mov_b32_e32 v153, v152
	s_nop 1
	v_permlane32_swap_b32_e32 v152, v153
	v_add_f32_e32 v152, v152, v153
	v_mov_b32_e32 v153, v152
	s_nop 1
	v_permlane16_swap_b32_e32 v152, v153
	v_add_f32_e32 v152, v152, v153
	s_nop 1
	v_mov_b32_dpp v153, v152 row_ror:8 row_mask:0xf bank_mask:0xf
	v_add_f32_e32 v152, v152, v153
	s_nop 1
	v_mov_b32_dpp v153, v152 row_ror:4 row_mask:0xf bank_mask:0xf
	v_add_f32_e32 v152, v152, v153
	s_nop 1
	v_mov_b32_dpp v153, v152 row_ror:2 row_mask:0xf bank_mask:0xf
	v_add_f32_e32 v152, v152, v153
	s_nop 1
	v_mov_b32_dpp v153, v152 row_ror:1 row_mask:0xf bank_mask:0xf
	v_add_f32_e32 v152, v152, v153
	v_mov_b32_e32 v153, 0x358637bd
	v_fmac_f32_e32 v153, 0x3a800000, v152
	v_rsq_f32_e32 v153, v153
	s_nop 0
	v_mul_f32_e32 v156, v40, v153
	v_mul_f32_e32 v157, v41, v153
	v_mul_f32_e32 v158, v42, v153
	v_mul_f32_e32 v159, v43, v153
	v_mul_f32_e32 v160, v44, v153
	v_mul_f32_e32 v161, v45, v153
	v_mul_f32_e32 v162, v46, v153
	v_mul_f32_e32 v163, v47, v153
	v_mul_f32_e32 v164, v48, v153
	v_mul_f32_e32 v165, v49, v153
	v_mul_f32_e32 v166, v50, v153
	v_mul_f32_e32 v167, v51, v153
	v_mul_f32_e32 v168, v52, v153
	v_mul_f32_e32 v169, v53, v153
	v_mul_f32_e32 v170, v54, v153
	v_mul_f32_e32 v171, v55, v153
	v_mul_f32_e32 v156, v156, v8
	v_mul_f32_e32 v157, v157, v9
	v_mul_f32_e32 v158, v158, v10
	v_mul_f32_e32 v159, v159, v11
	v_mul_f32_e32 v160, v160, v12
	v_mul_f32_e32 v161, v161, v13
	v_mul_f32_e32 v162, v162, v14
	v_mul_f32_e32 v163, v163, v15
	v_mul_f32_e32 v164, v164, v16
	v_mul_f32_e32 v165, v165, v17
	v_mul_f32_e32 v166, v166, v18
	v_mul_f32_e32 v167, v167, v19
	v_mul_f32_e32 v168, v168, v20
	v_mul_f32_e32 v169, v169, v21
	v_mul_f32_e32 v170, v170, v22
	v_mul_f32_e32 v171, v171, v23
	v_add_f32_e32 v40, 1.0, v72
	v_add_f32_e32 v41, 1.0, v73
	v_add_f32_e32 v42, 1.0, v74
	v_add_f32_e32 v43, 1.0, v75
	v_add_f32_e32 v44, 1.0, v76
	v_add_f32_e32 v45, 1.0, v77
	v_add_f32_e32 v46, 1.0, v78
	v_add_f32_e32 v47, 1.0, v79
	v_add_f32_e32 v48, 1.0, v80
	v_add_f32_e32 v49, 1.0, v81
	v_add_f32_e32 v50, 1.0, v82
	v_add_f32_e32 v51, 1.0, v83
	v_add_f32_e32 v52, 1.0, v84
	v_add_f32_e32 v53, 1.0, v85
	v_add_f32_e32 v54, 1.0, v86
	v_add_f32_e32 v55, 1.0, v87
	v_fma_f32 v156, v156, v40, v56
	v_fma_f32 v157, v157, v41, v57
	v_fma_f32 v158, v158, v42, v58
	v_fma_f32 v159, v159, v43, v59
	v_fma_f32 v160, v160, v44, v60
	v_fma_f32 v161, v161, v45, v61
	v_fma_f32 v162, v162, v46, v62
	v_fma_f32 v163, v163, v47, v63
	v_fma_f32 v164, v164, v48, v64
	v_fma_f32 v165, v165, v49, v65
	v_fma_f32 v166, v166, v50, v66
	v_fma_f32 v167, v167, v51, v67
	v_fma_f32 v168, v168, v52, v68
	v_fma_f32 v169, v169, v53, v69
	v_fma_f32 v170, v170, v54, v70
	v_fma_f32 v171, v171, v55, v71
	v_cvt_pk_bf16_f32 v156, v156, v157
	v_cvt_pk_bf16_f32 v157, v158, v159
	v_cvt_pk_bf16_f32 v158, v160, v161
	v_cvt_pk_bf16_f32 v159, v162, v163
	v_cvt_pk_bf16_f32 v160, v164, v165
	v_cvt_pk_bf16_f32 v161, v166, v167
	v_cvt_pk_bf16_f32 v162, v168, v169
	v_cvt_pk_bf16_f32 v163, v170, v171
	global_store_dwordx4 v5, v[156:159], s[28:29]
	global_store_dwordx4 v5, v[160:163], s[28:29] offset:1024
	s_add_u32 s22, s22, 0x800000
	s_addc_u32 s23, s23, 0
	s_add_u32 s28, s28, 0x800000
	s_addc_u32 s29, s29, 0
	global_load_dwordx4 v[24:27], v4, s[18:19] nt
	global_load_dwordx4 v[28:31], v4, s[18:19] offset:16 nt
	global_load_dwordx4 v[32:35], v4, s[18:19] offset:2048 nt
	global_load_dwordx4 v[36:39], v4, s[18:19] offset:2064 nt
	global_load_dwordx4 v[40:43], v4, s[26:27] nt
	global_load_dwordx4 v[44:47], v4, s[26:27] offset:16 nt
	global_load_dwordx4 v[48:51], v4, s[26:27] offset:2048 nt
	global_load_dwordx4 v[52:55], v4, s[26:27] offset:2064 nt
	global_load_dwordx4 v[56:59], v4, s[20:21]
	global_load_dwordx4 v[60:63], v4, s[20:21] offset:16
	global_load_dwordx4 v[64:67], v4, s[20:21] offset:2048
	global_load_dwordx4 v[68:71], v4, s[20:21] offset:2064
	global_load_dwordx4 v[72:75], v4, s[12:13]
	global_load_dwordx4 v[76:79], v4, s[12:13] offset:16
	global_load_dwordx4 v[80:83], v4, s[12:13] offset:2048
	global_load_dwordx4 v[84:87], v4, s[12:13] offset:2064
	s_add_u32 s18, s18, 0x1000000
	s_addc_u32 s19, s19, 0
	s_add_u32 s26, s26, 0x1000000
	s_addc_u32 s27, s27, 0
	s_add_u32 s20, s20, 0x6000
	s_addc_u32 s21, s21, 0
	s_add_u32 s12, s12, 0x6000
	s_addc_u32 s13, s13, 0
	s_waitcnt vmcnt(20)
	v_mul_f32_e32 v152, v88, v88
	v_fmac_f32_e32 v152, v89, v89
	v_fmac_f32_e32 v152, v90, v90
	v_fmac_f32_e32 v152, v91, v91
	v_fmac_f32_e32 v152, v92, v92
	v_fmac_f32_e32 v152, v93, v93
	v_fmac_f32_e32 v152, v94, v94
	v_fmac_f32_e32 v152, v95, v95
	v_fmac_f32_e32 v152, v96, v96
	v_fmac_f32_e32 v152, v97, v97
	v_fmac_f32_e32 v152, v98, v98
	v_fmac_f32_e32 v152, v99, v99
	v_fmac_f32_e32 v152, v100, v100
	v_fmac_f32_e32 v152, v101, v101
	v_fmac_f32_e32 v152, v102, v102
	v_fmac_f32_e32 v152, v103, v103
	v_mov_b32_e32 v153, v152
	s_nop 1
	v_permlane32_swap_b32_e32 v152, v153
	v_add_f32_e32 v152, v152, v153
	v_mov_b32_e32 v153, v152
	s_nop 1
	v_permlane16_swap_b32_e32 v152, v153
	v_add_f32_e32 v152, v152, v153
	s_nop 1
	v_mov_b32_dpp v153, v152 row_ror:8 row_mask:0xf bank_mask:0xf
	v_add_f32_e32 v152, v152, v153
	s_nop 1
	v_mov_b32_dpp v153, v152 row_ror:4 row_mask:0xf bank_mask:0xf
	v_add_f32_e32 v152, v152, v153
	s_nop 1
	v_mov_b32_dpp v153, v152 row_ror:2 row_mask:0xf bank_mask:0xf
	v_add_f32_e32 v152, v152, v153
	s_nop 1
	v_mov_b32_dpp v153, v152 row_ror:1 row_mask:0xf bank_mask:0xf
	v_add_f32_e32 v152, v152, v153
	v_mov_b32_e32 v153, 0x358637bd
	v_fmac_f32_e32 v153, 0x3a800000, v152
	v_rsq_f32_e32 v153, v153
	s_nop 0
	v_mul_f32_e32 v156, v88, v153
	v_mul_f32_e32 v157, v89, v153
	v_mul_f32_e32 v158, v90, v153
	v_mul_f32_e32 v159, v91, v153
	v_mul_f32_e32 v160, v92, v153
	v_mul_f32_e32 v161, v93, v153
	v_mul_f32_e32 v162, v94, v153
	v_mul_f32_e32 v163, v95, v153
	v_mul_f32_e32 v164, v96, v153
	v_mul_f32_e32 v165, v97, v153
	v_mul_f32_e32 v166, v98, v153
	v_mul_f32_e32 v167, v99, v153
	v_mul_f32_e32 v168, v100, v153
	v_mul_f32_e32 v169, v101, v153
	v_mul_f32_e32 v170, v102, v153
	v_mul_f32_e32 v171, v103, v153
	v_mul_f32_e32 v156, v156, v8
	v_mul_f32_e32 v157, v157, v9
	v_mul_f32_e32 v158, v158, v10
	v_mul_f32_e32 v159, v159, v11
	v_mul_f32_e32 v160, v160, v12
	v_mul_f32_e32 v161, v161, v13
	v_mul_f32_e32 v162, v162, v14
	v_mul_f32_e32 v163, v163, v15
	v_mul_f32_e32 v164, v164, v16
	v_mul_f32_e32 v165, v165, v17
	v_mul_f32_e32 v166, v166, v18
	v_mul_f32_e32 v167, v167, v19
	v_mul_f32_e32 v168, v168, v20
	v_mul_f32_e32 v169, v169, v21
	v_mul_f32_e32 v170, v170, v22
	v_mul_f32_e32 v171, v171, v23
	v_add_f32_e32 v88, 1.0, v136
	v_add_f32_e32 v89, 1.0, v137
	v_add_f32_e32 v90, 1.0, v138
	v_add_f32_e32 v91, 1.0, v139
	v_add_f32_e32 v92, 1.0, v140
	v_add_f32_e32 v93, 1.0, v141
	v_add_f32_e32 v94, 1.0, v142
	v_add_f32_e32 v95, 1.0, v143
	v_add_f32_e32 v96, 1.0, v144
	v_add_f32_e32 v97, 1.0, v145
	v_add_f32_e32 v98, 1.0, v146
	v_add_f32_e32 v99, 1.0, v147
	v_add_f32_e32 v100, 1.0, v148
	v_add_f32_e32 v101, 1.0, v149
	v_add_f32_e32 v102, 1.0, v150
	v_add_f32_e32 v103, 1.0, v151
	v_fma_f32 v156, v156, v88, v120
	v_fma_f32 v157, v157, v89, v121
	v_fma_f32 v158, v158, v90, v122
	v_fma_f32 v159, v159, v91, v123
	v_fma_f32 v160, v160, v92, v124
	v_fma_f32 v161, v161, v93, v125
	v_fma_f32 v162, v162, v94, v126
	v_fma_f32 v163, v163, v95, v127
	v_fma_f32 v164, v164, v96, v128
	v_fma_f32 v165, v165, v97, v129
	v_fma_f32 v166, v166, v98, v130
	v_fma_f32 v167, v167, v99, v131
	v_fma_f32 v168, v168, v100, v132
	v_fma_f32 v169, v169, v101, v133
	v_fma_f32 v170, v170, v102, v134
	v_fma_f32 v171, v171, v103, v135
	v_cvt_pk_bf16_f32 v156, v156, v157
	v_cvt_pk_bf16_f32 v157, v158, v159
	v_cvt_pk_bf16_f32 v158, v160, v161
	v_cvt_pk_bf16_f32 v159, v162, v163
	v_cvt_pk_bf16_f32 v160, v164, v165
	v_cvt_pk_bf16_f32 v161, v166, v167
	v_cvt_pk_bf16_f32 v162, v168, v169
	v_cvt_pk_bf16_f32 v163, v170, v171
	global_store_dwordx4 v5, v[156:159], s[22:23]
	global_store_dwordx4 v5, v[160:163], s[22:23] offset:1024
	v_mul_f32_e32 v152, v104, v104
	v_fmac_f32_e32 v152, v105, v105
	v_fmac_f32_e32 v152, v106, v106
	v_fmac_f32_e32 v152, v107, v107
	v_fmac_f32_e32 v152, v108, v108
	v_fmac_f32_e32 v152, v109, v109
	v_fmac_f32_e32 v152, v110, v110
	v_fmac_f32_e32 v152, v111, v111
	v_fmac_f32_e32 v152, v112, v112
	v_fmac_f32_e32 v152, v113, v113
	v_fmac_f32_e32 v152, v114, v114
	v_fmac_f32_e32 v152, v115, v115
	v_fmac_f32_e32 v152, v116, v116
	v_fmac_f32_e32 v152, v117, v117
	v_fmac_f32_e32 v152, v118, v118
	v_fmac_f32_e32 v152, v119, v119
	v_mov_b32_e32 v153, v152
	s_nop 1
	v_permlane32_swap_b32_e32 v152, v153
	v_add_f32_e32 v152, v152, v153
	v_mov_b32_e32 v153, v152
	s_nop 1
	v_permlane16_swap_b32_e32 v152, v153
	v_add_f32_e32 v152, v152, v153
	s_nop 1
	v_mov_b32_dpp v153, v152 row_ror:8 row_mask:0xf bank_mask:0xf
	v_add_f32_e32 v152, v152, v153
	s_nop 1
	v_mov_b32_dpp v153, v152 row_ror:4 row_mask:0xf bank_mask:0xf
	v_add_f32_e32 v152, v152, v153
	s_nop 1
	v_mov_b32_dpp v153, v152 row_ror:2 row_mask:0xf bank_mask:0xf
	v_add_f32_e32 v152, v152, v153
	s_nop 1
	v_mov_b32_dpp v153, v152 row_ror:1 row_mask:0xf bank_mask:0xf
	v_add_f32_e32 v152, v152, v153
	v_mov_b32_e32 v153, 0x358637bd
	v_fmac_f32_e32 v153, 0x3a800000, v152
	v_rsq_f32_e32 v153, v153
	s_nop 0
	v_mul_f32_e32 v156, v104, v153
	v_mul_f32_e32 v157, v105, v153
	v_mul_f32_e32 v158, v106, v153
	v_mul_f32_e32 v159, v107, v153
	v_mul_f32_e32 v160, v108, v153
	v_mul_f32_e32 v161, v109, v153
	v_mul_f32_e32 v162, v110, v153
	v_mul_f32_e32 v163, v111, v153
	v_mul_f32_e32 v164, v112, v153
	v_mul_f32_e32 v165, v113, v153
	v_mul_f32_e32 v166, v114, v153
	v_mul_f32_e32 v167, v115, v153
	v_mul_f32_e32 v168, v116, v153
	v_mul_f32_e32 v169, v117, v153
	v_mul_f32_e32 v170, v118, v153
	v_mul_f32_e32 v171, v119, v153
	v_mul_f32_e32 v156, v156, v8
	v_mul_f32_e32 v157, v157, v9
	v_mul_f32_e32 v158, v158, v10
	v_mul_f32_e32 v159, v159, v11
	v_mul_f32_e32 v160, v160, v12
	v_mul_f32_e32 v161, v161, v13
	v_mul_f32_e32 v162, v162, v14
	v_mul_f32_e32 v163, v163, v15
	v_mul_f32_e32 v164, v164, v16
	v_mul_f32_e32 v165, v165, v17
	v_mul_f32_e32 v166, v166, v18
	v_mul_f32_e32 v167, v167, v19
	v_mul_f32_e32 v168, v168, v20
	v_mul_f32_e32 v169, v169, v21
	v_mul_f32_e32 v170, v170, v22
	v_mul_f32_e32 v171, v171, v23
	v_add_f32_e32 v104, 1.0, v136
	v_add_f32_e32 v105, 1.0, v137
	v_add_f32_e32 v106, 1.0, v138
	v_add_f32_e32 v107, 1.0, v139
	v_add_f32_e32 v108, 1.0, v140
	v_add_f32_e32 v109, 1.0, v141
	v_add_f32_e32 v110, 1.0, v142
	v_add_f32_e32 v111, 1.0, v143
	v_add_f32_e32 v112, 1.0, v144
	v_add_f32_e32 v113, 1.0, v145
	v_add_f32_e32 v114, 1.0, v146
	v_add_f32_e32 v115, 1.0, v147
	v_add_f32_e32 v116, 1.0, v148
	v_add_f32_e32 v117, 1.0, v149
	v_add_f32_e32 v118, 1.0, v150
	v_add_f32_e32 v119, 1.0, v151
	v_fma_f32 v156, v156, v104, v120
	v_fma_f32 v157, v157, v105, v121
	v_fma_f32 v158, v158, v106, v122
	v_fma_f32 v159, v159, v107, v123
	v_fma_f32 v160, v160, v108, v124
	v_fma_f32 v161, v161, v109, v125
	v_fma_f32 v162, v162, v110, v126
	v_fma_f32 v163, v163, v111, v127
	v_fma_f32 v164, v164, v112, v128
	v_fma_f32 v165, v165, v113, v129
	v_fma_f32 v166, v166, v114, v130
	v_fma_f32 v167, v167, v115, v131
	v_fma_f32 v168, v168, v116, v132
	v_fma_f32 v169, v169, v117, v133
	v_fma_f32 v170, v170, v118, v134
	v_fma_f32 v171, v171, v119, v135
	v_cvt_pk_bf16_f32 v156, v156, v157
	v_cvt_pk_bf16_f32 v157, v158, v159
	v_cvt_pk_bf16_f32 v158, v160, v161
	v_cvt_pk_bf16_f32 v159, v162, v163
	v_cvt_pk_bf16_f32 v160, v164, v165
	v_cvt_pk_bf16_f32 v161, v166, v167
	v_cvt_pk_bf16_f32 v162, v168, v169
	v_cvt_pk_bf16_f32 v163, v170, v171
	global_store_dwordx4 v5, v[156:159], s[28:29]
	global_store_dwordx4 v5, v[160:163], s[28:29] offset:1024
	s_add_u32 s22, s22, 0x800000
	s_addc_u32 s23, s23, 0
	s_add_u32 s28, s28, 0x800000
	s_addc_u32 s29, s29, 0
	global_load_dwordx4 v[88:91], v4, s[18:19] nt
	global_load_dwordx4 v[92:95], v4, s[18:19] offset:16 nt
	global_load_dwordx4 v[96:99], v4, s[18:19] offset:2048 nt
	global_load_dwordx4 v[100:103], v4, s[18:19] offset:2064 nt
	global_load_dwordx4 v[104:107], v4, s[26:27] nt
	global_load_dwordx4 v[108:111], v4, s[26:27] offset:16 nt
	global_load_dwordx4 v[112:115], v4, s[26:27] offset:2048 nt
	global_load_dwordx4 v[116:119], v4, s[26:27] offset:2064 nt
	global_load_dwordx4 v[120:123], v4, s[20:21]
	global_load_dwordx4 v[124:127], v4, s[20:21] offset:16
	global_load_dwordx4 v[128:131], v4, s[20:21] offset:2048
	global_load_dwordx4 v[132:135], v4, s[20:21] offset:2064
	global_load_dwordx4 v[136:139], v4, s[12:13]
	global_load_dwordx4 v[140:143], v4, s[12:13] offset:16
	global_load_dwordx4 v[144:147], v4, s[12:13] offset:2048
	global_load_dwordx4 v[148:151], v4, s[12:13] offset:2064
	s_add_u32 s20, s20, 0x6000
	s_addc_u32 s21, s21, 0
	s_add_u32 s12, s12, 0x6000
	s_addc_u32 s13, s13, 0
	s_waitcnt vmcnt(20)
	v_mul_f32_e32 v152, v24, v24
	v_fmac_f32_e32 v152, v25, v25
	v_fmac_f32_e32 v152, v26, v26
	v_fmac_f32_e32 v152, v27, v27
	v_fmac_f32_e32 v152, v28, v28
	v_fmac_f32_e32 v152, v29, v29
	v_fmac_f32_e32 v152, v30, v30
	v_fmac_f32_e32 v152, v31, v31
	v_fmac_f32_e32 v152, v32, v32
	v_fmac_f32_e32 v152, v33, v33
	v_fmac_f32_e32 v152, v34, v34
	v_fmac_f32_e32 v152, v35, v35
	v_fmac_f32_e32 v152, v36, v36
	v_fmac_f32_e32 v152, v37, v37
	v_fmac_f32_e32 v152, v38, v38
	v_fmac_f32_e32 v152, v39, v39
	v_mov_b32_e32 v153, v152
	s_nop 1
	v_permlane32_swap_b32_e32 v152, v153
	v_add_f32_e32 v152, v152, v153
	v_mov_b32_e32 v153, v152
	s_nop 1
	v_permlane16_swap_b32_e32 v152, v153
	v_add_f32_e32 v152, v152, v153
	s_nop 1
	v_mov_b32_dpp v153, v152 row_ror:8 row_mask:0xf bank_mask:0xf
	v_add_f32_e32 v152, v152, v153
	s_nop 1
	v_mov_b32_dpp v153, v152 row_ror:4 row_mask:0xf bank_mask:0xf
	v_add_f32_e32 v152, v152, v153
	s_nop 1
	v_mov_b32_dpp v153, v152 row_ror:2 row_mask:0xf bank_mask:0xf
	v_add_f32_e32 v152, v152, v153
	s_nop 1
	v_mov_b32_dpp v153, v152 row_ror:1 row_mask:0xf bank_mask:0xf
	v_add_f32_e32 v152, v152, v153
	v_mov_b32_e32 v153, 0x358637bd
	v_fmac_f32_e32 v153, 0x3a800000, v152
	v_rsq_f32_e32 v153, v153
	s_nop 0
	v_mul_f32_e32 v156, v24, v153
	v_mul_f32_e32 v157, v25, v153
	v_mul_f32_e32 v158, v26, v153
	v_mul_f32_e32 v159, v27, v153
	v_mul_f32_e32 v160, v28, v153
	v_mul_f32_e32 v161, v29, v153
	v_mul_f32_e32 v162, v30, v153
	v_mul_f32_e32 v163, v31, v153
	v_mul_f32_e32 v164, v32, v153
	v_mul_f32_e32 v165, v33, v153
	v_mul_f32_e32 v166, v34, v153
	v_mul_f32_e32 v167, v35, v153
	v_mul_f32_e32 v168, v36, v153
	v_mul_f32_e32 v169, v37, v153
	v_mul_f32_e32 v170, v38, v153
	v_mul_f32_e32 v171, v39, v153
	v_mul_f32_e32 v156, v156, v8
	v_mul_f32_e32 v157, v157, v9
	v_mul_f32_e32 v158, v158, v10
	v_mul_f32_e32 v159, v159, v11
	v_mul_f32_e32 v160, v160, v12
	v_mul_f32_e32 v161, v161, v13
	v_mul_f32_e32 v162, v162, v14
	v_mul_f32_e32 v163, v163, v15
	v_mul_f32_e32 v164, v164, v16
	v_mul_f32_e32 v165, v165, v17
	v_mul_f32_e32 v166, v166, v18
	v_mul_f32_e32 v167, v167, v19
	v_mul_f32_e32 v168, v168, v20
	v_mul_f32_e32 v169, v169, v21
	v_mul_f32_e32 v170, v170, v22
	v_mul_f32_e32 v171, v171, v23
	v_add_f32_e32 v24, 1.0, v72
	v_add_f32_e32 v25, 1.0, v73
	v_add_f32_e32 v26, 1.0, v74
	v_add_f32_e32 v27, 1.0, v75
	v_add_f32_e32 v28, 1.0, v76
	v_add_f32_e32 v29, 1.0, v77
	v_add_f32_e32 v30, 1.0, v78
	v_add_f32_e32 v31, 1.0, v79
	v_add_f32_e32 v32, 1.0, v80
	v_add_f32_e32 v33, 1.0, v81
	v_add_f32_e32 v34, 1.0, v82
	v_add_f32_e32 v35, 1.0, v83
	v_add_f32_e32 v36, 1.0, v84
	v_add_f32_e32 v37, 1.0, v85
	v_add_f32_e32 v38, 1.0, v86
	v_add_f32_e32 v39, 1.0, v87
	v_fma_f32 v156, v156, v24, v56
	v_fma_f32 v157, v157, v25, v57
	v_fma_f32 v158, v158, v26, v58
	v_fma_f32 v159, v159, v27, v59
	v_fma_f32 v160, v160, v28, v60
	v_fma_f32 v161, v161, v29, v61
	v_fma_f32 v162, v162, v30, v62
	v_fma_f32 v163, v163, v31, v63
	v_fma_f32 v164, v164, v32, v64
	v_fma_f32 v165, v165, v33, v65
	v_fma_f32 v166, v166, v34, v66
	v_fma_f32 v167, v167, v35, v67
	v_fma_f32 v168, v168, v36, v68
	v_fma_f32 v169, v169, v37, v69
	v_fma_f32 v170, v170, v38, v70
	v_fma_f32 v171, v171, v39, v71
	v_cvt_pk_bf16_f32 v156, v156, v157
	v_cvt_pk_bf16_f32 v157, v158, v159
	v_cvt_pk_bf16_f32 v158, v160, v161
	v_cvt_pk_bf16_f32 v159, v162, v163
	v_cvt_pk_bf16_f32 v160, v164, v165
	v_cvt_pk_bf16_f32 v161, v166, v167
	v_cvt_pk_bf16_f32 v162, v168, v169
	v_cvt_pk_bf16_f32 v163, v170, v171
	global_store_dwordx4 v5, v[156:159], s[22:23]
	global_store_dwordx4 v5, v[160:163], s[22:23] offset:1024
	v_mul_f32_e32 v152, v40, v40
	v_fmac_f32_e32 v152, v41, v41
	v_fmac_f32_e32 v152, v42, v42
	v_fmac_f32_e32 v152, v43, v43
	v_fmac_f32_e32 v152, v44, v44
	v_fmac_f32_e32 v152, v45, v45
	v_fmac_f32_e32 v152, v46, v46
	v_fmac_f32_e32 v152, v47, v47
	v_fmac_f32_e32 v152, v48, v48
	v_fmac_f32_e32 v152, v49, v49
	v_fmac_f32_e32 v152, v50, v50
	v_fmac_f32_e32 v152, v51, v51
	v_fmac_f32_e32 v152, v52, v52
	v_fmac_f32_e32 v152, v53, v53
	v_fmac_f32_e32 v152, v54, v54
	v_fmac_f32_e32 v152, v55, v55
	v_mov_b32_e32 v153, v152
	s_nop 1
	v_permlane32_swap_b32_e32 v152, v153
	v_add_f32_e32 v152, v152, v153
	v_mov_b32_e32 v153, v152
	s_nop 1
	v_permlane16_swap_b32_e32 v152, v153
	v_add_f32_e32 v152, v152, v153
	s_nop 1
	v_mov_b32_dpp v153, v152 row_ror:8 row_mask:0xf bank_mask:0xf
	v_add_f32_e32 v152, v152, v153
	s_nop 1
	v_mov_b32_dpp v153, v152 row_ror:4 row_mask:0xf bank_mask:0xf
	v_add_f32_e32 v152, v152, v153
	s_nop 1
	v_mov_b32_dpp v153, v152 row_ror:2 row_mask:0xf bank_mask:0xf
	v_add_f32_e32 v152, v152, v153
	s_nop 1
	v_mov_b32_dpp v153, v152 row_ror:1 row_mask:0xf bank_mask:0xf
	v_add_f32_e32 v152, v152, v153
	v_mov_b32_e32 v153, 0x358637bd
	v_fmac_f32_e32 v153, 0x3a800000, v152
	v_rsq_f32_e32 v153, v153
	s_nop 0
	v_mul_f32_e32 v156, v40, v153
	v_mul_f32_e32 v157, v41, v153
	v_mul_f32_e32 v158, v42, v153
	v_mul_f32_e32 v159, v43, v153
	v_mul_f32_e32 v160, v44, v153
	v_mul_f32_e32 v161, v45, v153
	v_mul_f32_e32 v162, v46, v153
	v_mul_f32_e32 v163, v47, v153
	v_mul_f32_e32 v164, v48, v153
	v_mul_f32_e32 v165, v49, v153
	v_mul_f32_e32 v166, v50, v153
	v_mul_f32_e32 v167, v51, v153
	v_mul_f32_e32 v168, v52, v153
	v_mul_f32_e32 v169, v53, v153
	v_mul_f32_e32 v170, v54, v153
	v_mul_f32_e32 v171, v55, v153
	v_mul_f32_e32 v156, v156, v8
	v_mul_f32_e32 v157, v157, v9
	v_mul_f32_e32 v158, v158, v10
	v_mul_f32_e32 v159, v159, v11
	v_mul_f32_e32 v160, v160, v12
	v_mul_f32_e32 v161, v161, v13
	v_mul_f32_e32 v162, v162, v14
	v_mul_f32_e32 v163, v163, v15
	v_mul_f32_e32 v164, v164, v16
	v_mul_f32_e32 v165, v165, v17
	v_mul_f32_e32 v166, v166, v18
	v_mul_f32_e32 v167, v167, v19
	v_mul_f32_e32 v168, v168, v20
	v_mul_f32_e32 v169, v169, v21
	v_mul_f32_e32 v170, v170, v22
	v_mul_f32_e32 v171, v171, v23
	v_add_f32_e32 v40, 1.0, v72
	v_add_f32_e32 v41, 1.0, v73
	v_add_f32_e32 v42, 1.0, v74
	v_add_f32_e32 v43, 1.0, v75
	v_add_f32_e32 v44, 1.0, v76
	v_add_f32_e32 v45, 1.0, v77
	v_add_f32_e32 v46, 1.0, v78
	v_add_f32_e32 v47, 1.0, v79
	v_add_f32_e32 v48, 1.0, v80
	v_add_f32_e32 v49, 1.0, v81
	v_add_f32_e32 v50, 1.0, v82
	v_add_f32_e32 v51, 1.0, v83
	v_add_f32_e32 v52, 1.0, v84
	v_add_f32_e32 v53, 1.0, v85
	v_add_f32_e32 v54, 1.0, v86
	v_add_f32_e32 v55, 1.0, v87
	v_fma_f32 v156, v156, v40, v56
	v_fma_f32 v157, v157, v41, v57
	v_fma_f32 v158, v158, v42, v58
	v_fma_f32 v159, v159, v43, v59
	v_fma_f32 v160, v160, v44, v60
	v_fma_f32 v161, v161, v45, v61
	v_fma_f32 v162, v162, v46, v62
	v_fma_f32 v163, v163, v47, v63
	v_fma_f32 v164, v164, v48, v64
	v_fma_f32 v165, v165, v49, v65
	v_fma_f32 v166, v166, v50, v66
	v_fma_f32 v167, v167, v51, v67
	v_fma_f32 v168, v168, v52, v68
	v_fma_f32 v169, v169, v53, v69
	v_fma_f32 v170, v170, v54, v70
	v_fma_f32 v171, v171, v55, v71
	v_cvt_pk_bf16_f32 v156, v156, v157
	v_cvt_pk_bf16_f32 v157, v158, v159
	v_cvt_pk_bf16_f32 v158, v160, v161
	v_cvt_pk_bf16_f32 v159, v162, v163
	v_cvt_pk_bf16_f32 v160, v164, v165
	v_cvt_pk_bf16_f32 v161, v166, v167
	v_cvt_pk_bf16_f32 v162, v168, v169
	v_cvt_pk_bf16_f32 v163, v170, v171
	global_store_dwordx4 v5, v[156:159], s[28:29]
	global_store_dwordx4 v5, v[160:163], s[28:29] offset:1024
	s_add_u32 s22, s22, 0x800000
	s_addc_u32 s23, s23, 0
	s_add_u32 s28, s28, 0x800000
	s_addc_u32 s29, s29, 0
	global_load_dwordx4 v[24:27], v4, s[10:11] nt
	global_load_dwordx4 v[28:31], v4, s[10:11] offset:16 nt
	global_load_dwordx4 v[32:35], v4, s[10:11] offset:2048 nt
	global_load_dwordx4 v[36:39], v4, s[10:11] offset:2064 nt
	global_load_dwordx4 v[56:59], v4, s[20:21]
	global_load_dwordx4 v[60:63], v4, s[20:21] offset:16
	global_load_dwordx4 v[64:67], v4, s[20:21] offset:2048
	global_load_dwordx4 v[68:71], v4, s[20:21] offset:2064
	global_load_dwordx4 v[72:75], v4, s[12:13]
	global_load_dwordx4 v[76:79], v4, s[12:13] offset:16
	global_load_dwordx4 v[80:83], v4, s[12:13] offset:2048
	global_load_dwordx4 v[84:87], v4, s[12:13] offset:2064
	s_add_u32 s20, s20, 0x6000
	s_addc_u32 s21, s21, 0
	s_add_u32 s12, s12, 0x6000
	s_addc_u32 s13, s13, 0
	s_waitcnt vmcnt(16)
	v_mul_f32_e32 v152, v88, v88
	v_fmac_f32_e32 v152, v89, v89
	v_fmac_f32_e32 v152, v90, v90
	v_fmac_f32_e32 v152, v91, v91
	v_fmac_f32_e32 v152, v92, v92
	v_fmac_f32_e32 v152, v93, v93
	v_fmac_f32_e32 v152, v94, v94
	v_fmac_f32_e32 v152, v95, v95
	v_fmac_f32_e32 v152, v96, v96
	v_fmac_f32_e32 v152, v97, v97
	v_fmac_f32_e32 v152, v98, v98
	v_fmac_f32_e32 v152, v99, v99
	v_fmac_f32_e32 v152, v100, v100
	v_fmac_f32_e32 v152, v101, v101
	v_fmac_f32_e32 v152, v102, v102
	v_fmac_f32_e32 v152, v103, v103
	v_mov_b32_e32 v153, v152
	s_nop 1
	v_permlane32_swap_b32_e32 v152, v153
	v_add_f32_e32 v152, v152, v153
	v_mov_b32_e32 v153, v152
	s_nop 1
	v_permlane16_swap_b32_e32 v152, v153
	v_add_f32_e32 v152, v152, v153
	s_nop 1
	v_mov_b32_dpp v153, v152 row_ror:8 row_mask:0xf bank_mask:0xf
	v_add_f32_e32 v152, v152, v153
	s_nop 1
	v_mov_b32_dpp v153, v152 row_ror:4 row_mask:0xf bank_mask:0xf
	v_add_f32_e32 v152, v152, v153
	s_nop 1
	v_mov_b32_dpp v153, v152 row_ror:2 row_mask:0xf bank_mask:0xf
	v_add_f32_e32 v152, v152, v153
	s_nop 1
	v_mov_b32_dpp v153, v152 row_ror:1 row_mask:0xf bank_mask:0xf
	v_add_f32_e32 v152, v152, v153
	v_mov_b32_e32 v153, 0x358637bd
	v_fmac_f32_e32 v153, 0x3a800000, v152
	v_rsq_f32_e32 v153, v153
	s_nop 0
	v_mul_f32_e32 v156, v88, v153
	v_mul_f32_e32 v157, v89, v153
	v_mul_f32_e32 v158, v90, v153
	v_mul_f32_e32 v159, v91, v153
	v_mul_f32_e32 v160, v92, v153
	v_mul_f32_e32 v161, v93, v153
	v_mul_f32_e32 v162, v94, v153
	v_mul_f32_e32 v163, v95, v153
	v_mul_f32_e32 v164, v96, v153
	v_mul_f32_e32 v165, v97, v153
	v_mul_f32_e32 v166, v98, v153
	v_mul_f32_e32 v167, v99, v153
	v_mul_f32_e32 v168, v100, v153
	v_mul_f32_e32 v169, v101, v153
	v_mul_f32_e32 v170, v102, v153
	v_mul_f32_e32 v171, v103, v153
	v_mul_f32_e32 v156, v156, v8
	v_mul_f32_e32 v157, v157, v9
	v_mul_f32_e32 v158, v158, v10
	v_mul_f32_e32 v159, v159, v11
	v_mul_f32_e32 v160, v160, v12
	v_mul_f32_e32 v161, v161, v13
	v_mul_f32_e32 v162, v162, v14
	v_mul_f32_e32 v163, v163, v15
	v_mul_f32_e32 v164, v164, v16
	v_mul_f32_e32 v165, v165, v17
	v_mul_f32_e32 v166, v166, v18
	v_mul_f32_e32 v167, v167, v19
	v_mul_f32_e32 v168, v168, v20
	v_mul_f32_e32 v169, v169, v21
	v_mul_f32_e32 v170, v170, v22
	v_mul_f32_e32 v171, v171, v23
	v_add_f32_e32 v88, 1.0, v136
	v_add_f32_e32 v89, 1.0, v137
	v_add_f32_e32 v90, 1.0, v138
	v_add_f32_e32 v91, 1.0, v139
	v_add_f32_e32 v92, 1.0, v140
	v_add_f32_e32 v93, 1.0, v141
	v_add_f32_e32 v94, 1.0, v142
	v_add_f32_e32 v95, 1.0, v143
	v_add_f32_e32 v96, 1.0, v144
	v_add_f32_e32 v97, 1.0, v145
	v_add_f32_e32 v98, 1.0, v146
	v_add_f32_e32 v99, 1.0, v147
	v_add_f32_e32 v100, 1.0, v148
	v_add_f32_e32 v101, 1.0, v149
	v_add_f32_e32 v102, 1.0, v150
	v_add_f32_e32 v103, 1.0, v151
	v_fma_f32 v156, v156, v88, v120
	v_fma_f32 v157, v157, v89, v121
	v_fma_f32 v158, v158, v90, v122
	v_fma_f32 v159, v159, v91, v123
	v_fma_f32 v160, v160, v92, v124
	v_fma_f32 v161, v161, v93, v125
	v_fma_f32 v162, v162, v94, v126
	v_fma_f32 v163, v163, v95, v127
	v_fma_f32 v164, v164, v96, v128
	v_fma_f32 v165, v165, v97, v129
	v_fma_f32 v166, v166, v98, v130
	v_fma_f32 v167, v167, v99, v131
	v_fma_f32 v168, v168, v100, v132
	v_fma_f32 v169, v169, v101, v133
	v_fma_f32 v170, v170, v102, v134
	v_fma_f32 v171, v171, v103, v135
	v_cvt_pk_bf16_f32 v156, v156, v157
	v_cvt_pk_bf16_f32 v157, v158, v159
	v_cvt_pk_bf16_f32 v158, v160, v161
	v_cvt_pk_bf16_f32 v159, v162, v163
	v_cvt_pk_bf16_f32 v160, v164, v165
	v_cvt_pk_bf16_f32 v161, v166, v167
	v_cvt_pk_bf16_f32 v162, v168, v169
	v_cvt_pk_bf16_f32 v163, v170, v171
	global_store_dwordx4 v5, v[156:159], s[22:23]
	global_store_dwordx4 v5, v[160:163], s[22:23] offset:1024
	v_mul_f32_e32 v152, v104, v104
	v_fmac_f32_e32 v152, v105, v105
	v_fmac_f32_e32 v152, v106, v106
	v_fmac_f32_e32 v152, v107, v107
	v_fmac_f32_e32 v152, v108, v108
	v_fmac_f32_e32 v152, v109, v109
	v_fmac_f32_e32 v152, v110, v110
	v_fmac_f32_e32 v152, v111, v111
	v_fmac_f32_e32 v152, v112, v112
	v_fmac_f32_e32 v152, v113, v113
	v_fmac_f32_e32 v152, v114, v114
	v_fmac_f32_e32 v152, v115, v115
	v_fmac_f32_e32 v152, v116, v116
	v_fmac_f32_e32 v152, v117, v117
	v_fmac_f32_e32 v152, v118, v118
	v_fmac_f32_e32 v152, v119, v119
	v_mov_b32_e32 v153, v152
	s_nop 1
	v_permlane32_swap_b32_e32 v152, v153
	v_add_f32_e32 v152, v152, v153
	v_mov_b32_e32 v153, v152
	s_nop 1
	v_permlane16_swap_b32_e32 v152, v153
	v_add_f32_e32 v152, v152, v153
	s_nop 1
	v_mov_b32_dpp v153, v152 row_ror:8 row_mask:0xf bank_mask:0xf
	v_add_f32_e32 v152, v152, v153
	s_nop 1
	v_mov_b32_dpp v153, v152 row_ror:4 row_mask:0xf bank_mask:0xf
	v_add_f32_e32 v152, v152, v153
	s_nop 1
	v_mov_b32_dpp v153, v152 row_ror:2 row_mask:0xf bank_mask:0xf
	v_add_f32_e32 v152, v152, v153
	s_nop 1
	v_mov_b32_dpp v153, v152 row_ror:1 row_mask:0xf bank_mask:0xf
	v_add_f32_e32 v152, v152, v153
	v_mov_b32_e32 v153, 0x358637bd
	v_fmac_f32_e32 v153, 0x3a800000, v152
	v_rsq_f32_e32 v153, v153
	s_nop 0
	v_mul_f32_e32 v156, v104, v153
	v_mul_f32_e32 v157, v105, v153
	v_mul_f32_e32 v158, v106, v153
	v_mul_f32_e32 v159, v107, v153
	v_mul_f32_e32 v160, v108, v153
	v_mul_f32_e32 v161, v109, v153
	v_mul_f32_e32 v162, v110, v153
	v_mul_f32_e32 v163, v111, v153
	v_mul_f32_e32 v164, v112, v153
	v_mul_f32_e32 v165, v113, v153
	v_mul_f32_e32 v166, v114, v153
	v_mul_f32_e32 v167, v115, v153
	v_mul_f32_e32 v168, v116, v153
	v_mul_f32_e32 v169, v117, v153
	v_mul_f32_e32 v170, v118, v153
	v_mul_f32_e32 v171, v119, v153
	v_mul_f32_e32 v156, v156, v8
	v_mul_f32_e32 v157, v157, v9
	v_mul_f32_e32 v158, v158, v10
	v_mul_f32_e32 v159, v159, v11
	v_mul_f32_e32 v160, v160, v12
	v_mul_f32_e32 v161, v161, v13
	v_mul_f32_e32 v162, v162, v14
	v_mul_f32_e32 v163, v163, v15
	v_mul_f32_e32 v164, v164, v16
	v_mul_f32_e32 v165, v165, v17
	v_mul_f32_e32 v166, v166, v18
	v_mul_f32_e32 v167, v167, v19
	v_mul_f32_e32 v168, v168, v20
	v_mul_f32_e32 v169, v169, v21
	v_mul_f32_e32 v170, v170, v22
	v_mul_f32_e32 v171, v171, v23
	v_add_f32_e32 v104, 1.0, v136
	v_add_f32_e32 v105, 1.0, v137
	v_add_f32_e32 v106, 1.0, v138
	v_add_f32_e32 v107, 1.0, v139
	v_add_f32_e32 v108, 1.0, v140
	v_add_f32_e32 v109, 1.0, v141
	v_add_f32_e32 v110, 1.0, v142
	v_add_f32_e32 v111, 1.0, v143
	v_add_f32_e32 v112, 1.0, v144
	v_add_f32_e32 v113, 1.0, v145
	v_add_f32_e32 v114, 1.0, v146
	v_add_f32_e32 v115, 1.0, v147
	v_add_f32_e32 v116, 1.0, v148
	v_add_f32_e32 v117, 1.0, v149
	v_add_f32_e32 v118, 1.0, v150
	v_add_f32_e32 v119, 1.0, v151
	v_fma_f32 v156, v156, v104, v120
	v_fma_f32 v157, v157, v105, v121
	v_fma_f32 v158, v158, v106, v122
	v_fma_f32 v159, v159, v107, v123
	v_fma_f32 v160, v160, v108, v124
	v_fma_f32 v161, v161, v109, v125
	v_fma_f32 v162, v162, v110, v126
	v_fma_f32 v163, v163, v111, v127
	v_fma_f32 v164, v164, v112, v128
	v_fma_f32 v165, v165, v113, v129
	v_fma_f32 v166, v166, v114, v130
	v_fma_f32 v167, v167, v115, v131
	v_fma_f32 v168, v168, v116, v132
	v_fma_f32 v169, v169, v117, v133
	v_fma_f32 v170, v170, v118, v134
	v_fma_f32 v171, v171, v119, v135
	v_cvt_pk_bf16_f32 v156, v156, v157
	v_cvt_pk_bf16_f32 v157, v158, v159
	v_cvt_pk_bf16_f32 v158, v160, v161
	v_cvt_pk_bf16_f32 v159, v162, v163
	v_cvt_pk_bf16_f32 v160, v164, v165
	v_cvt_pk_bf16_f32 v161, v166, v167
	v_cvt_pk_bf16_f32 v162, v168, v169
	v_cvt_pk_bf16_f32 v163, v170, v171
	global_store_dwordx4 v5, v[156:159], s[28:29]
	global_store_dwordx4 v5, v[160:163], s[28:29] offset:1024
	s_add_u32 s22, s22, 0x800000
	s_addc_u32 s23, s23, 0
	s_add_u32 s28, s28, 0x800000
	s_addc_u32 s29, s29, 0
	s_waitcnt vmcnt(4)
	v_mul_f32_e32 v152, v24, v24
	v_fmac_f32_e32 v152, v25, v25
	v_fmac_f32_e32 v152, v26, v26
	v_fmac_f32_e32 v152, v27, v27
	v_fmac_f32_e32 v152, v28, v28
	v_fmac_f32_e32 v152, v29, v29
	v_fmac_f32_e32 v152, v30, v30
	v_fmac_f32_e32 v152, v31, v31
	v_fmac_f32_e32 v152, v32, v32
	v_fmac_f32_e32 v152, v33, v33
	v_fmac_f32_e32 v152, v34, v34
	v_fmac_f32_e32 v152, v35, v35
	v_fmac_f32_e32 v152, v36, v36
	v_fmac_f32_e32 v152, v37, v37
	v_fmac_f32_e32 v152, v38, v38
	v_fmac_f32_e32 v152, v39, v39
	v_mov_b32_e32 v153, v152
	s_nop 1
	v_permlane32_swap_b32_e32 v152, v153
	v_add_f32_e32 v152, v152, v153
	v_mov_b32_e32 v153, v152
	s_nop 1
	v_permlane16_swap_b32_e32 v152, v153
	v_add_f32_e32 v152, v152, v153
	s_nop 1
	v_mov_b32_dpp v153, v152 row_ror:8 row_mask:0xf bank_mask:0xf
	v_add_f32_e32 v152, v152, v153
	s_nop 1
	v_mov_b32_dpp v153, v152 row_ror:4 row_mask:0xf bank_mask:0xf
	v_add_f32_e32 v152, v152, v153
	s_nop 1
	v_mov_b32_dpp v153, v152 row_ror:2 row_mask:0xf bank_mask:0xf
	v_add_f32_e32 v152, v152, v153
	s_nop 1
	v_mov_b32_dpp v153, v152 row_ror:1 row_mask:0xf bank_mask:0xf
	v_add_f32_e32 v152, v152, v153
	v_mov_b32_e32 v153, 0x358637bd
	v_fmac_f32_e32 v153, 0x3a800000, v152
	v_rsq_f32_e32 v153, v153
	s_nop 0
	v_mul_f32_e32 v156, v24, v153
	v_mul_f32_e32 v157, v25, v153
	v_mul_f32_e32 v158, v26, v153
	v_mul_f32_e32 v159, v27, v153
	v_mul_f32_e32 v160, v28, v153
	v_mul_f32_e32 v161, v29, v153
	v_mul_f32_e32 v162, v30, v153
	v_mul_f32_e32 v163, v31, v153
	v_mul_f32_e32 v164, v32, v153
	v_mul_f32_e32 v165, v33, v153
	v_mul_f32_e32 v166, v34, v153
	v_mul_f32_e32 v167, v35, v153
	v_mul_f32_e32 v168, v36, v153
	v_mul_f32_e32 v169, v37, v153
	v_mul_f32_e32 v170, v38, v153
	v_mul_f32_e32 v171, v39, v153
	v_mul_f32_e32 v156, v156, v8
	v_mul_f32_e32 v157, v157, v9
	v_mul_f32_e32 v158, v158, v10
	v_mul_f32_e32 v159, v159, v11
	v_mul_f32_e32 v160, v160, v12
	v_mul_f32_e32 v161, v161, v13
	v_mul_f32_e32 v162, v162, v14
	v_mul_f32_e32 v163, v163, v15
	v_mul_f32_e32 v164, v164, v16
	v_mul_f32_e32 v165, v165, v17
	v_mul_f32_e32 v166, v166, v18
	v_mul_f32_e32 v167, v167, v19
	v_mul_f32_e32 v168, v168, v20
	v_mul_f32_e32 v169, v169, v21
	v_mul_f32_e32 v170, v170, v22
	v_mul_f32_e32 v171, v171, v23
	v_add_f32_e32 v24, 1.0, v72
	v_add_f32_e32 v25, 1.0, v73
	v_add_f32_e32 v26, 1.0, v74
	v_add_f32_e32 v27, 1.0, v75
	v_add_f32_e32 v28, 1.0, v76
	v_add_f32_e32 v29, 1.0, v77
	v_add_f32_e32 v30, 1.0, v78
	v_add_f32_e32 v31, 1.0, v79
	v_add_f32_e32 v32, 1.0, v80
	v_add_f32_e32 v33, 1.0, v81
	v_add_f32_e32 v34, 1.0, v82
	v_add_f32_e32 v35, 1.0, v83
	v_add_f32_e32 v36, 1.0, v84
	v_add_f32_e32 v37, 1.0, v85
	v_add_f32_e32 v38, 1.0, v86
	v_add_f32_e32 v39, 1.0, v87
	v_fma_f32 v156, v156, v24, v56
	v_fma_f32 v157, v157, v25, v57
	v_fma_f32 v158, v158, v26, v58
	v_fma_f32 v159, v159, v27, v59
	v_fma_f32 v160, v160, v28, v60
	v_fma_f32 v161, v161, v29, v61
	v_fma_f32 v162, v162, v30, v62
	v_fma_f32 v163, v163, v31, v63
	v_fma_f32 v164, v164, v32, v64
	v_fma_f32 v165, v165, v33, v65
	v_fma_f32 v166, v166, v34, v66
	v_fma_f32 v167, v167, v35, v67
	v_fma_f32 v168, v168, v36, v68
	v_fma_f32 v169, v169, v37, v69
	v_fma_f32 v170, v170, v38, v70
	v_fma_f32 v171, v171, v39, v71
	v_cvt_pk_bf16_f32 v156, v156, v157
	v_cvt_pk_bf16_f32 v157, v158, v159
	v_cvt_pk_bf16_f32 v158, v160, v161
	v_cvt_pk_bf16_f32 v159, v162, v163
	v_cvt_pk_bf16_f32 v160, v164, v165
	v_cvt_pk_bf16_f32 v161, v166, v167
	v_cvt_pk_bf16_f32 v162, v168, v169
	v_cvt_pk_bf16_f32 v163, v170, v171
	global_store_dwordx4 v5, v[156:159], s[2:3]
	global_store_dwordx4 v5, v[160:163], s[2:3] offset:1024

.LBB0_1961:
	v_lshl_add_u64 v[28:29], v[16:17], 0, v[8:9]
	v_lshl_add_u64 v[22:23], v[18:19], 0, v[8:9]
	global_load_dword v30, v[10:11], off
	global_load_dword v35, v[10:11], off offset:64
	global_load_dword v65, v[12:13], off
	global_load_dword v66, v[12:13], off offset:64
	global_load_dwordx4 v[0:3], v[14:15], off offset:16
	global_load_dwordx4 v[4:7], v[14:15], off
	global_load_dwordx4 v[24:27], v[22:23], off offset:-1024 nt
	global_load_dwordx4 v[36:39], v[22:23], off nt
	v_add_co_u32_e32 v22, vcc, 0x8800000, v28
	v_lshl_add_u64 v[16:17], v[16:17], 0, s[4:5]
	s_nop 0
	v_addc_co_u32_e32 v23, vcc, 0, v29, vcc
	v_add_co_u32_e32 v56, vcc, s11, v28
	global_load_dwordx4 v[40:43], v[22:23], off nt
	global_load_dwordx4 v[44:47], v[22:23], off offset:1024 nt
	v_addc_co_u32_e32 v57, vcc, 0, v29, vcc
	v_add_co_u32_e32 v28, vcc, s12, v28
	global_load_dwordx4 v[48:51], v[56:57], off nt
	global_load_dwordx4 v[52:55], v[56:57], off offset:1024 nt
	v_addc_co_u32_e32 v29, vcc, 0, v29, vcc
	global_load_dwordx4 v[56:59], v[28:29], off nt
	global_load_dwordx4 v[60:63], v[28:29], off offset:1024 nt
	v_lshl_add_u64 v[18:19], v[18:19], 0, s[6:7]
	s_waitcnt vmcnt(12)
	v_add_f32_e32 v64, v30, v35
	s_waitcnt vmcnt(10)
	v_add_f32_e32 v30, v65, v66
	s_waitcnt vmcnt(7)
	v_lshlrev_b32_e32 v66, 16, v24
	v_and_b32_e32 v67, 0xffff0000, v24
	v_lshlrev_b32_e32 v68, 16, v25
	v_and_b32_e32 v69, 0xffff0000, v25
	v_lshlrev_b32_e32 v72, 16, v27
	v_and_b32_e32 v73, 0xffff0000, v27
	v_lshlrev_b32_e32 v70, 16, v26
	v_and_b32_e32 v71, 0xffff0000, v26
	s_waitcnt vmcnt(5)
	v_lshlrev_b32_e32 v80, 16, v42
	v_and_b32_e32 v81, 0xffff0000, v42
	v_lshlrev_b32_e32 v42, 16, v43
	v_and_b32_e32 v43, 0xffff0000, v43
	v_lshlrev_b32_e32 v78, 16, v40
	s_waitcnt vmcnt(3)
	v_lshlrev_b32_e32 v88, 16, v50
	v_and_b32_e32 v89, 0xffff0000, v50
	v_lshlrev_b32_e32 v50, 16, v51
	v_and_b32_e32 v51, 0xffff0000, v51
	v_and_b32_e32 v79, 0xffff0000, v40
	v_lshlrev_b32_e32 v40, 16, v41
	v_and_b32_e32 v41, 0xffff0000, v41
	v_lshlrev_b32_e32 v86, 16, v48
	v_and_b32_e32 v87, 0xffff0000, v48
	v_lshlrev_b32_e32 v48, 16, v49
	v_and_b32_e32 v49, 0xffff0000, v49
	s_waitcnt vmcnt(1)
	v_lshlrev_b32_e32 v24, 16, v56
	v_and_b32_e32 v25, 0xffff0000, v56
	v_lshlrev_b32_e32 v28, 16, v57
	v_and_b32_e32 v29, 0xffff0000, v57
	v_lshlrev_b32_e32 v56, 16, v58
	v_and_b32_e32 v57, 0xffff0000, v58
	v_lshlrev_b32_e32 v58, 16, v59
	v_and_b32_e32 v59, 0xffff0000, v59
	v_pk_add_f32 v[42:43], v[42:43], v[50:51]
	v_lshlrev_b32_e32 v82, 16, v44
	v_and_b32_e32 v83, 0xffff0000, v44
	v_lshlrev_b32_e32 v44, 16, v45
	v_and_b32_e32 v45, 0xffff0000, v45
	v_lshlrev_b32_e32 v84, 16, v46
	v_and_b32_e32 v85, 0xffff0000, v46
	v_lshlrev_b32_e32 v46, 16, v47
	v_and_b32_e32 v47, 0xffff0000, v47
	v_lshlrev_b32_e32 v90, 16, v52
	v_and_b32_e32 v91, 0xffff0000, v52
	v_lshlrev_b32_e32 v52, 16, v53
	v_and_b32_e32 v53, 0xffff0000, v53
	v_lshlrev_b32_e32 v92, 16, v54
	v_and_b32_e32 v93, 0xffff0000, v54
	v_lshlrev_b32_e32 v54, 16, v55
	v_and_b32_e32 v55, 0xffff0000, v55
	v_pk_add_f32 v[50:51], v[80:81], v[88:89]
	v_pk_add_f32 v[40:41], v[40:41], v[48:49]
	v_pk_add_f32 v[48:49], v[78:79], v[86:87]
	v_pk_fma_f32 v[42:43], v[64:65], v[72:73], v[42:43] op_sel_hi:[0,1,1]
	v_mul_f32_e32 v65, 0xbfb8aa3b, v59
	v_lshlrev_b32_e32 v74, 16, v36
	v_and_b32_e32 v75, 0xffff0000, v36
	v_lshlrev_b32_e32 v36, 16, v37
	v_and_b32_e32 v37, 0xffff0000, v37
	v_lshlrev_b32_e32 v76, 16, v38
	v_and_b32_e32 v77, 0xffff0000, v38
	v_lshlrev_b32_e32 v38, 16, v39
	v_and_b32_e32 v39, 0xffff0000, v39
	s_waitcnt vmcnt(0)
	v_lshlrev_b32_e32 v26, 16, v60
	v_and_b32_e32 v27, 0xffff0000, v60
	v_lshlrev_b32_e32 v94, 16, v62
	v_and_b32_e32 v95, 0xffff0000, v62
	v_lshlrev_b32_e32 v62, 16, v63
	v_and_b32_e32 v63, 0xffff0000, v63
	v_pk_add_f32 v[46:47], v[46:47], v[54:55]
	v_pk_add_f32 v[54:55], v[84:85], v[92:93]
	v_pk_add_f32 v[44:45], v[44:45], v[52:53]
	v_pk_add_f32 v[52:53], v[82:83], v[90:91]
	v_pk_fma_f32 v[50:51], v[64:65], v[70:71], v[50:51] op_sel_hi:[0,1,1]
	v_pk_fma_f32 v[40:41], v[64:65], v[68:69], v[40:41] op_sel_hi:[0,1,1]
	v_mul_f32_e32 v69, 0xbfb8aa3b, v24
	v_pk_fma_f32 v[48:49], v[64:65], v[66:67], v[48:49] op_sel_hi:[0,1,1]
	v_mul_f32_e32 v64, 0xbfb8aa3b, v25
	v_lshlrev_b32_e32 v60, 16, v61
	v_and_b32_e32 v61, 0xffff0000, v61
	v_mul_f32_e32 v72, 0xbfb8aa3b, v56
	v_mul_f32_e32 v70, 0xbfb8aa3b, v57
	v_mul_f32_e32 v71, 0xbfb8aa3b, v28
	v_mul_f32_e32 v66, 0xbfb8aa3b, v62
	v_pk_fma_f32 v[38:39], v[30:31], v[38:39], v[46:47] op_sel_hi:[0,1,1]
	v_mul_f32_e32 v67, 0xbfb8aa3b, v63
	v_mul_f32_e32 v73, 0xbfb8aa3b, v94
	v_pk_fma_f32 v[46:47], v[30:31], v[76:77], v[54:55] op_sel_hi:[0,1,1]
	v_pk_fma_f32 v[36:37], v[30:31], v[36:37], v[44:45] op_sel_hi:[0,1,1]
	v_mul_f32_e32 v77, 0xbfb8aa3b, v26
	v_pk_fma_f32 v[44:45], v[30:31], v[74:75], v[52:53] op_sel_hi:[0,1,1]
	v_mul_f32_e32 v30, 0xbfb8aa3b, v27
	v_exp_f32_e32 v69, v69
	v_exp_f32_e32 v64, v64
	v_mul_f32_e32 v35, 0xbfb8aa3b, v58
	v_mul_f32_e32 v68, 0xbfb8aa3b, v29
	v_mul_f32_e32 v54, 0xbfb8aa3b, v95
	v_mul_f32_e32 v55, 0xbfb8aa3b, v60
	v_mul_f32_e32 v76, 0xbfb8aa3b, v61
	v_exp_f32_e32 v52, v65
	v_exp_f32_e32 v53, v72
	v_exp_f32_e32 v65, v70
	v_exp_f32_e32 v70, v71
	v_exp_f32_e32 v66, v66
	v_exp_f32_e32 v67, v67
	v_exp_f32_e32 v71, v73
	v_exp_f32_e32 v73, v77
	v_exp_f32_e32 v30, v30
	v_exp_f32_e32 v35, v35
	v_exp_f32_e32 v68, v68
	v_exp_f32_e32 v54, v54
	v_exp_f32_e32 v55, v55
	v_exp_f32_e32 v72, v76
	v_add_f32_e32 v69, 1.0, v69
	v_add_f32_e32 v76, 1.0, v64
	v_add_f32_e32 v74, 1.0, v52
	v_add_f32_e32 v75, 1.0, v53
	v_add_f32_e32 v77, 1.0, v66
	v_add_f32_e32 v78, 1.0, v67
	v_add_f32_e32 v82, 1.0, v73
	v_add_f32_e32 v30, 1.0, v30
	v_rcp_f32_e32 v66, v69
	v_rcp_f32_e32 v67, v76
	v_add_f32_e32 v35, 1.0, v35
	v_add_f32_e32 v65, 1.0, v65
	v_add_f32_e32 v70, 1.0, v70
	v_add_f32_e32 v68, 1.0, v68
	v_add_f32_e32 v79, 1.0, v54
	v_add_f32_e32 v80, 1.0, v55
	v_add_f32_e32 v81, 1.0, v72
	v_rcp_f32_e32 v53, v74
	v_rcp_f32_e32 v54, v75
	v_rcp_f32_e32 v74, v82
	v_rcp_f32_e32 v75, v30
	v_rcp_f32_e32 v52, v35
	v_rcp_f32_e32 v55, v65
	v_rcp_f32_e32 v64, v70
	v_rcp_f32_e32 v65, v68
	v_rcp_f32_e32 v72, v80
	v_rcp_f32_e32 v73, v81
	v_add_f32_e32 v71, 1.0, v71
	v_pk_mul_f32 v[24:25], v[66:67], v[24:25]
	v_rcp_f32_e32 v70, v71
	v_rcp_f32_e32 v71, v79
	v_pk_mul_f32 v[26:27], v[74:75], v[26:27]
	v_pk_mul_f32 v[24:25], v[24:25], v[48:49]
	v_rcp_f32_e32 v68, v77
	v_rcp_f32_e32 v69, v78
	v_pk_mul_f32 v[52:53], v[52:53], v[58:59]
	v_pk_mul_f32 v[28:29], v[64:65], v[28:29]
	v_pk_mul_f32 v[60:61], v[72:73], v[60:61]
	v_pk_mul_f32 v[26:27], v[26:27], v[44:45]
	v_mul_f32_e32 v30, v25, v25
	v_pk_mul_f32 v[42:43], v[52:53], v[42:43]
	v_pk_mul_f32 v[28:29], v[28:29], v[40:41]
	v_pk_mul_f32 v[36:37], v[60:61], v[36:37]
	v_mul_f32_e32 v52, v27, v27
	v_pk_fma_f32 v[60:61], v[24:25], v[24:25], v[30:31] op_sel_hi:[1,1,0]
	v_pk_mul_f32 v[54:55], v[54:55], v[56:57]
	v_mul_f32_e32 v44, v29, v29
	v_pk_fma_f32 v[52:53], v[26:27], v[26:27], v[52:53] op_sel_hi:[1,1,0]
	v_pk_fma_f32 v[60:61], v[28:29], v[28:29], v[60:61]
	v_pk_mul_f32 v[58:59], v[70:71], v[94:95]
	v_pk_mul_f32 v[50:51], v[54:55], v[50:51]
	v_mul_f32_e32 v54, v37, v37
	v_pk_fma_f32 v[52:53], v[36:37], v[36:37], v[52:53]
	v_pk_add_f32 v[44:45], v[44:45], v[60:61] op_sel_hi:[0,1]
	v_pk_mul_f32 v[56:57], v[68:69], v[62:63]
	v_pk_mul_f32 v[40:41], v[58:59], v[46:47]
	v_mul_f32_e32 v46, v51, v51
	v_pk_add_f32 v[52:53], v[54:55], v[52:53] op_sel_hi:[0,1]
	v_pk_fma_f32 v[44:45], v[50:51], v[50:51], v[44:45]
	v_pk_mul_f32 v[38:39], v[56:57], v[38:39]
	v_mul_f32_e32 v56, v41, v41
	v_pk_fma_f32 v[52:53], v[40:41], v[40:41], v[52:53]
	v_pk_add_f32 v[44:45], v[46:47], v[44:45] op_sel_hi:[0,1]
	v_mul_f32_e32 v48, v43, v43
	v_pk_add_f32 v[46:47], v[56:57], v[52:53] op_sel_hi:[0,1]
	v_pk_fma_f32 v[44:45], v[42:43], v[42:43], v[44:45]
	v_mul_f32_e32 v58, v39, v39
	v_pk_fma_f32 v[46:47], v[38:39], v[38:39], v[46:47]
	v_pk_add_f32 v[44:45], v[48:49], v[44:45] op_sel_hi:[0,1]
	v_pk_add_f32 v[46:47], v[58:59], v[46:47] op_sel_hi:[0,1]
	v_mov_b32_e32 v49, v44
	v_mov_b32_e32 v48, v46
	s_nop 0
	v_permlane16_swap_b32_e32 v44, v49
	v_permlane16_swap_b32_e32 v46, v48
	v_mov_b32_e32 v47, v44
	v_pk_add_f32 v[44:45], v[46:47], v[48:49]
	s_nop 1
	v_mov_b32_dpp v47, v45 row_ror:8 row_mask:0xf bank_mask:0xf
	s_nop 1
	v_mov_b32_dpp v46, v44 row_ror:8 row_mask:0xf bank_mask:0xf
	s_waitcnt lgkmcnt(0)
	v_pk_add_f32 v[44:45], v[44:45], v[46:47]
	s_nop 1
	v_mov_b32_dpp v47, v45 row_ror:4 row_mask:0xf bank_mask:0xf
	s_nop 1
	v_mov_b32_dpp v46, v44 row_ror:4 row_mask:0xf bank_mask:0xf
	s_waitcnt lgkmcnt(0)
	v_pk_add_f32 v[44:45], v[44:45], v[46:47]
	s_nop 1
	v_mov_b32_dpp v47, v45 row_ror:2 row_mask:0xf bank_mask:0xf
	s_nop 1
	v_mov_b32_dpp v46, v44 row_ror:2 row_mask:0xf bank_mask:0xf
	s_waitcnt lgkmcnt(0)
	v_pk_add_f32 v[44:45], v[44:45], v[46:47]
	s_nop 1
	v_mov_b32_dpp v47, v45 row_ror:1 row_mask:0xf bank_mask:0xf
	s_nop 1
	v_mov_b32_dpp v46, v44 row_ror:1 row_mask:0xf bank_mask:0xf
	s_waitcnt lgkmcnt(0)
	v_pk_add_f32 v[44:45], v[44:45], v[46:47]
	s_nop 0
	v_pk_fma_f32 v[44:45], v[44:45], s[10:11], v[20:21] op_sel_hi:[1,0,0]
	v_add_u32_e32 v21, s66, v21
	v_mul_f32_e32 v30, 0x4b800000, v45
	v_cmp_gt_f32_e32 vcc, s13, v45
	s_nop 1
	v_cndmask_b32_e32 v30, v45, v30, vcc
	v_rsq_f32_e32 v30, v30
	s_nop 0
	v_mul_f32_e32 v35, 0x45800000, v30
	v_cndmask_b32_e32 v30, v30, v35, vcc
	v_pk_mul_f32 v[24:25], v[24:25], v[30:31] op_sel_hi:[1,0]
	v_pk_mul_f32 v[28:29], v[28:29], v[30:31] op_sel_hi:[1,0]
	v_pk_mul_f32 v[46:47], v[50:51], v[30:31] op_sel_hi:[1,0]
	v_pk_mul_f32 v[42:43], v[42:43], v[30:31] op_sel_hi:[1,0]
	v_pk_mul_f32 v[4:5], v[24:25], v[4:5]
	v_pk_mul_f32 v[6:7], v[28:29], v[6:7]
	v_pk_mul_f32 v[24:25], v[46:47], v[0:1]
	v_pk_mul_f32 v[28:29], v[42:43], v[2:3]
	v_cvt_pk_bf16_f32 v0, v4, v5
	v_cvt_pk_bf16_f32 v1, v6, v7
	v_cvt_pk_bf16_f32 v2, v24, v25
	v_cvt_pk_bf16_f32 v3, v28, v29
	global_store_dwordx4 v[22:23], v[0:3], off
	global_load_dwordx4 v[0:3], v[14:15], off offset:2048
	s_nop 0
	global_load_dwordx4 v[4:7], v[14:15], off offset:2064
	v_cmp_lt_i32_e32 vcc, s14, v21
	s_or_b64 s[8:9], vcc, s[8:9]
	v_mul_f32_e32 v24, 0x4b800000, v44
	v_cmp_gt_f32_e32 vcc, s13, v44
	s_nop 1
	v_cndmask_b32_e32 v24, v44, v24, vcc
	v_rsq_f32_e32 v24, v24
	s_nop 0
	v_mul_f32_e32 v25, 0x45800000, v24
	v_cndmask_b32_e32 v24, v24, v25, vcc
	v_pk_mul_f32 v[26:27], v[26:27], v[24:25] op_sel_hi:[1,0]
	v_pk_mul_f32 v[28:29], v[36:37], v[24:25] op_sel_hi:[1,0]
	v_pk_mul_f32 v[36:37], v[40:41], v[24:25] op_sel_hi:[1,0]
	v_pk_mul_f32 v[24:25], v[38:39], v[24:25] op_sel_hi:[1,0]
	s_waitcnt vmcnt(1)
	v_pk_mul_f32 v[0:1], v[26:27], v[0:1]
	v_pk_mul_f32 v[2:3], v[28:29], v[2:3]
	s_waitcnt vmcnt(0)
	v_pk_mul_f32 v[4:5], v[36:37], v[4:5]
	v_pk_mul_f32 v[6:7], v[24:25], v[6:7]
	v_cvt_pk_bf16_f32 v0, v0, v1
	v_cvt_pk_bf16_f32 v1, v2, v3
	v_cvt_pk_bf16_f32 v2, v4, v5
	v_cvt_pk_bf16_f32 v3, v6, v7
	global_store_dwordx4 v[22:23], v[0:3], off offset:1024
	s_andn2_b64 exec, exec, s[8:9]
	s_cbranch_execnz .LBB0_1961
